# speedup vs baseline: 1.0131x; 1.0131x over previous
; DEV void phase_gemm(const u16* A, const u16* Bt, u16* C, int ntiles, int N, int K, unsigned char* smem, int epi, const GateEpi& ge) {
;   const int nN = N >> 8;
;   const int lb = (blockIdx.x & 7) * (gridDim.x >> 3) + (blockIdx.x >> 3);
;   const int nig = 8 * nN;
;   int gid = 0, rem = lb;
;   for (int t = lb; t < ntiles; t += gridDim.x) {
;     while (rem >= nig) { rem -= nig; ++gid; }
;     const int pm = gid * 8 + (rem & 7), pn = rem >> 3;
.LBB0_626:
	s_cmp_ge_i32 s65, s43
	s_cbranch_scc1 .LBB0_818
	s_lshr_b32 s45, s18, 6
	s_xor_b64 s[2:3], s[6:7], -1
	s_lshr_b32 s42, s44, 5
	s_lshl_b64 s[16:17], s[18:19], 8
	s_add_i32 s45, s45, -2
	v_mul_u32_u24_e64 v131, s44, 13
	s_mov_b32 s46, 0
	s_mov_b32 s47, s65
	s_mov_b32 s48, s65
	s_branch .LBB0_629
.LBB0_629:
	s_cmp_lt_i32 s47, s42
	s_cbranch_scc1 .LBB0_631

; #define STAGE(P, q) do { GLDS16(q[0], (unsigned char*)(P) + wid * 1024); GLDS16(q[1], (unsigned char*)(P) + wid * 1024 + 8192); \
;     q[0] += 128; q[1] += 128; asm volatile("" : "+v"(q[0]), "+v"(q[1])); } while (0)
; #define LDA(dst, b, h) _Pragma("unroll") for (int m = 0; m < 4; ++m) _Pragma("unroll") for (int k = 0; k < 2; ++k) \
;     dst[m][k] = *(const bf16x8*)((const unsigned char*)SA(b, h) + lds_byte1(wr * 64 + m * 16 + fr, k * 32 + fq * 8))
; #define LDB(dst, b, h) _Pragma("unroll") for (int n = 0; n < 2; ++n) _Pragma("unroll") for (int k = 0; k < 2; ++k) \
;     dst[n][k] = *(const bf16x8*)((const unsigned char*)SB(b, h) + lds_byte1(wc * 32 + n * 16 + fr, k * 32 + fq * 8))
; #define MMA(ai, bj, At_, Bt_) do { __builtin_amdgcn_s_setprio(1); \
;     _Pragma("unroll") for (int m = 0; m < 4; ++m) _Pragma("unroll") for (int n = 0; n < 2; ++n) _Pragma("unroll") for (int k = 0; k < 2; ++k) \
;       acc[ai][bj][m][n] = mfma16(At_[m][k], Bt_[n][k], acc[ai][bj][m][n]); \
;     __builtin_amdgcn_s_setprio(0); } while (0)
; #define WAIT_V(n) asm volatile("s_waitcnt vmcnt(" #n ")" ::: "memory")
; #define WAIT_L(n) asm volatile("s_waitcnt lgkmcnt(" #n ")" ::: "memory")
; #define BAR __builtin_amdgcn_s_barrier()
; #define SCHED __builtin_amdgcn_sched_barrier(0)
; DEV void gemm_tile(const u16* __restrict__ A, const u16* __restrict__ Bt, u16* __restrict__ C, int N, int K,
;                    int brow, int bcol, unsigned char* smem, int epi, const GateEpi& ge) {
;     ...
;     LDB(B0, 0, 0); SCHED; LDA(At, 0, 0); STAGE(SA(1, 1), qA1);
;     WAIT_L(8); BAR; WAIT_L(0); MMA(0, 0, At, B0); BAR; SCHED;
;     LDB(B1, 0, 1); STAGE(SB(0, 0), qB0);
;     BAR; WAIT_L(0); MMA(0, 1, At, B1); BAR;
;     LDA(At, 0, 1); STAGE(SA(0, 0), qA0);
;     BAR; WAIT_L(0); MMA(1, 0, At, B0); BAR; SCHED;
;     STAGE(SB(0, 1), qB1);
;     WAIT_V(6); BAR; MMA(1, 1, At, B1); BAR;
.LBB0_634:
	ds_read_b128 v[156:159], v152
	ds_read_b128 v[180:183], v152 offset:1024
	ds_read_b128 v[184:187], v152 offset:256
	ds_read_b128 v[188:191], v152 offset:1280
	s_mov_b32 m0, s56
	v_add_u32_e32 v153, s53, v151
	v_add_u32_e32 v154, s54, v151
	v_add_u32_e32 v155, s55, v151
	ds_read_b128 v[192:195], v128
	ds_read_b128 v[196:199], v128 offset:1024
	ds_read_b128 v[200:203], v153
	ds_read_b128 v[204:207], v153 offset:1024
	ds_read_b128 v[208:211], v154
	ds_read_b128 v[212:215], v154 offset:1024
	ds_read_b128 v[216:219], v155
	ds_read_b128 v[220:223], v155 offset:1024
	global_load_lds_dwordx4 v[132:133], off
	s_mov_b32 m0, s52
	v_lshl_add_u64 v[236:237], v[132:133], 0, s[8:9]
	global_load_lds_dwordx4 v[134:135], off
	v_lshl_add_u64 v[238:239], v[134:135], 0, s[8:9]
	s_waitcnt lgkmcnt(8)
	s_barrier
	s_waitcnt lgkmcnt(0)
	s_setprio 1
	s_waitcnt lgkmcnt(0)
	v_mfma_f32_16x16x32_bf16 v[124:127], v[156:159], v[192:195], v[124:127]
	v_mfma_f32_16x16x32_bf16 v[120:123], v[184:187], v[192:195], v[120:123]
	v_mfma_f32_16x16x32_bf16 v[116:119], v[156:159], v[200:203], v[116:119]
	v_mfma_f32_16x16x32_bf16 v[112:115], v[184:187], v[200:203], v[112:115]
	v_mfma_f32_16x16x32_bf16 v[108:111], v[156:159], v[208:211], v[108:111]
	v_mfma_f32_16x16x32_bf16 v[104:107], v[184:187], v[208:211], v[104:107]
	v_mfma_f32_16x16x32_bf16 v[100:103], v[156:159], v[216:219], v[100:103]
	v_mfma_f32_16x16x32_bf16 v[96:99], v[184:187], v[216:219], v[96:99]
	v_mfma_f32_16x16x32_bf16 v[124:127], v[180:183], v[196:199], v[124:127]
	v_mfma_f32_16x16x32_bf16 v[120:123], v[188:191], v[196:199], v[120:123]
	v_mfma_f32_16x16x32_bf16 v[116:119], v[180:183], v[204:207], v[116:119]
	v_mfma_f32_16x16x32_bf16 v[112:115], v[188:191], v[204:207], v[112:115]
	v_mfma_f32_16x16x32_bf16 v[108:111], v[180:183], v[212:215], v[108:111]
	v_mfma_f32_16x16x32_bf16 v[104:107], v[188:191], v[212:215], v[104:107]
	v_mfma_f32_16x16x32_bf16 v[100:103], v[180:183], v[220:223], v[100:103]
	v_mfma_f32_16x16x32_bf16 v[96:99], v[188:191], v[220:223], v[96:99]
	s_setprio 0
	s_barrier
	s_mov_b32 m0, s4
	ds_read_b128 v[132:135], v150
	ds_read_b128 v[224:227], v150 offset:1024
	ds_read_b128 v[228:231], v150 offset:256
	ds_read_b128 v[232:235], v150 offset:1280
	global_load_lds_dwordx4 v[136:137], off
	s_mov_b32 m0, s5
	v_lshl_add_u64 v[240:241], v[136:137], 0, s[8:9]
	global_load_lds_dwordx4 v[138:139], off
	v_lshl_add_u64 v[242:243], v[138:139], 0, s[8:9]
	s_barrier
	s_waitcnt lgkmcnt(0)
	s_setprio 1
	s_waitcnt lgkmcnt(0)
	v_mfma_f32_16x16x32_bf16 v[84:87], v[132:135], v[192:195], v[84:87]
	v_mfma_f32_16x16x32_bf16 v[68:71], v[228:231], v[192:195], v[68:71]
	v_mfma_f32_16x16x32_bf16 v[52:55], v[132:135], v[200:203], v[52:55]
	v_mfma_f32_16x16x32_bf16 v[48:51], v[228:231], v[200:203], v[48:51]
	v_mfma_f32_16x16x32_bf16 v[44:47], v[132:135], v[208:211], v[44:47]
	v_mfma_f32_16x16x32_bf16 v[40:43], v[228:231], v[208:211], v[40:43]
	v_mfma_f32_16x16x32_bf16 v[36:39], v[132:135], v[216:219], v[36:39]
	v_mfma_f32_16x16x32_bf16 v[32:35], v[228:231], v[216:219], v[32:35]
	v_mfma_f32_16x16x32_bf16 v[84:87], v[224:227], v[196:199], v[84:87]
	v_mfma_f32_16x16x32_bf16 v[68:71], v[232:235], v[196:199], v[68:71]
	v_mfma_f32_16x16x32_bf16 v[52:55], v[224:227], v[204:207], v[52:55]
	v_mfma_f32_16x16x32_bf16 v[48:51], v[232:235], v[204:207], v[48:51]
	v_mfma_f32_16x16x32_bf16 v[44:47], v[224:227], v[212:215], v[44:47]
	v_mfma_f32_16x16x32_bf16 v[40:43], v[232:235], v[212:215], v[40:43]
	v_mfma_f32_16x16x32_bf16 v[36:39], v[224:227], v[220:223], v[36:39]
	v_mfma_f32_16x16x32_bf16 v[32:35], v[232:235], v[220:223], v[32:35]
	s_setprio 0
	s_mov_b32 m0, s1
	s_barrier
	ds_read_b128 v[136:139], v128 offset:16384
	ds_read_b128 v[192:195], v128 offset:17408
	ds_read_b128 v[196:199], v153 offset:16384
	ds_read_b128 v[200:203], v153 offset:17408
	ds_read_b128 v[204:207], v154 offset:16384
	ds_read_b128 v[208:211], v154 offset:17408
	ds_read_b128 v[212:215], v155 offset:16384
	ds_read_b128 v[216:219], v155 offset:17408
	global_load_lds_dwordx4 v[140:141], off
	s_mov_b32 m0, s6
	v_lshl_add_u64 v[244:245], v[140:141], 0, s[8:9]
	global_load_lds_dwordx4 v[142:143], off
	v_lshl_add_u64 v[246:247], v[142:143], 0, s[8:9]
	s_barrier
	s_waitcnt lgkmcnt(0)
	s_setprio 1
	s_waitcnt lgkmcnt(0)
	v_mfma_f32_16x16x32_bf16 v[28:31], v[156:159], v[136:139], v[28:31]
	v_mfma_f32_16x16x32_bf16 v[24:27], v[184:187], v[136:139], v[24:27]
	v_mfma_f32_16x16x32_bf16 v[20:23], v[156:159], v[196:199], v[20:23]
	v_mfma_f32_16x16x32_bf16 v[16:19], v[184:187], v[196:199], v[16:19]
	v_mfma_f32_16x16x32_bf16 v[12:15], v[156:159], v[204:207], v[12:15]
	v_mfma_f32_16x16x32_bf16 v[8:11], v[184:187], v[204:207], v[8:11]
	v_mfma_f32_16x16x32_bf16 v[4:7], v[156:159], v[212:215], v[4:7]
	v_mfma_f32_16x16x32_bf16 v[0:3], v[184:187], v[212:215], v[0:3]
	v_mfma_f32_16x16x32_bf16 v[28:31], v[180:183], v[192:195], v[28:31]
	v_mfma_f32_16x16x32_bf16 v[24:27], v[188:191], v[192:195], v[24:27]
	v_mfma_f32_16x16x32_bf16 v[20:23], v[180:183], v[200:203], v[20:23]
	v_mfma_f32_16x16x32_bf16 v[16:19], v[188:191], v[200:203], v[16:19]
	v_mfma_f32_16x16x32_bf16 v[12:15], v[180:183], v[208:211], v[12:15]
	v_mfma_f32_16x16x32_bf16 v[8:11], v[188:191], v[208:211], v[8:11]
	v_mfma_f32_16x16x32_bf16 v[4:7], v[180:183], v[216:219], v[4:7]
	v_mfma_f32_16x16x32_bf16 v[0:3], v[188:191], v[216:219], v[0:3]
	s_setprio 0
	s_barrier
	s_mov_b32 m0, s7
	v_lshl_add_u64 v[248:249], v[144:145], 0, s[8:9]
	global_load_lds_dwordx4 v[144:145], off
	s_mov_b32 m0, s35
	v_lshl_add_u64 v[250:251], v[146:147], 0, s[8:9]
	global_load_lds_dwordx4 v[146:147], off
	s_waitcnt vmcnt(6)
	s_barrier
; #define STAGE(P, q) do { GLDS16(q[0], (unsigned char*)(P) + wid * 1024); GLDS16(q[1], (unsigned char*)(P) + wid * 1024 + 8192); \
;     q[0] += 128; q[1] += 128; asm volatile("" : "+v"(q[0]), "+v"(q[1])); } while (0)
; #define LDA(dst, b, h) _Pragma("unroll") for (int m = 0; m < 4; ++m) _Pragma("unroll") for (int k = 0; k < 2; ++k) \
;     dst[m][k] = *(const bf16x8*)((const unsigned char*)SA(b, h) + lds_byte1(wr * 64 + m * 16 + fr, k * 32 + fq * 8))
; #define LDB(dst, b, h) _Pragma("unroll") for (int n = 0; n < 2; ++n) _Pragma("unroll") for (int k = 0; k < 2; ++k) \
;     dst[n][k] = *(const bf16x8*)((const unsigned char*)SB(b, h) + lds_byte1(wc * 32 + n * 16 + fr, k * 32 + fq * 8))
; #define MMA(ai, bj, At_, Bt_) do { __builtin_amdgcn_s_setprio(1); \
;     _Pragma("unroll") for (int m = 0; m < 4; ++m) _Pragma("unroll") for (int n = 0; n < 2; ++n) _Pragma("unroll") for (int k = 0; k < 2; ++k) \
;       acc[ai][bj][m][n] = mfma16(At_[m][k], Bt_[n][k], acc[ai][bj][m][n]); \
;     __builtin_amdgcn_s_setprio(0); } while (0)
; #define WAIT_V(n) asm volatile("s_waitcnt vmcnt(" #n ")" ::: "memory")
; #define WAIT_L(n) asm volatile("s_waitcnt lgkmcnt(" #n ")" ::: "memory")
; #define BAR __builtin_amdgcn_s_barrier()
; #define SCHED __builtin_amdgcn_sched_barrier(0)
; DEV void gemm_tile(const u16* __restrict__ A, const u16* __restrict__ Bt, u16* __restrict__ C, int N, int K,
;                    int brow, int bcol, unsigned char* smem, int epi, const GateEpi& ge) {
;     ...
;     WAIT_V(6); BAR; MMA(1, 1, At, B1); BAR;
;     LDB(B0, 1, 0); SCHED; LDA(At, 1, 0); STAGE(SA(0, 1), qA1);
;     WAIT_L(8); BAR; WAIT_L(0); MMA(0, 0, At, B0); BAR; SCHED;
;     LDB(B1, 1, 1); STAGE(SB(1, 0), qB0);
;     BAR; WAIT_L(0); MMA(0, 1, At, B1); BAR;
;     LDA(At, 1, 1); STAGE(SA(1, 0), qA0);
;     BAR; WAIT_L(0); MMA(1, 0, At, B0); BAR; SCHED;
;     STAGE(SB(1, 1), qB1);
;     WAIT_V(6); BAR; MMA(1, 1, At, B1); BAR;
	s_setprio 1
	v_mfma_f32_16x16x32_bf16 v[56:59], v[132:135], v[136:139], v[56:59]
	v_mfma_f32_16x16x32_bf16 v[60:63], v[228:231], v[136:139], v[60:63]
	v_mfma_f32_16x16x32_bf16 v[64:67], v[132:135], v[196:199], v[64:67]
	v_mfma_f32_16x16x32_bf16 v[72:75], v[228:231], v[196:199], v[72:75]
	v_mfma_f32_16x16x32_bf16 v[76:79], v[132:135], v[204:207], v[76:79]
	v_mfma_f32_16x16x32_bf16 v[80:83], v[228:231], v[204:207], v[80:83]
	v_mfma_f32_16x16x32_bf16 v[88:91], v[132:135], v[212:215], v[88:91]
	v_mfma_f32_16x16x32_bf16 v[92:95], v[228:231], v[212:215], v[92:95]
	v_mfma_f32_16x16x32_bf16 v[56:59], v[224:227], v[192:195], v[56:59]
	v_mfma_f32_16x16x32_bf16 v[60:63], v[232:235], v[192:195], v[60:63]
	v_mfma_f32_16x16x32_bf16 v[64:67], v[224:227], v[200:203], v[64:67]
	v_mfma_f32_16x16x32_bf16 v[72:75], v[232:235], v[200:203], v[72:75]
	v_mfma_f32_16x16x32_bf16 v[76:79], v[224:227], v[208:211], v[76:79]
	v_mfma_f32_16x16x32_bf16 v[80:83], v[232:235], v[208:211], v[80:83]
	v_mfma_f32_16x16x32_bf16 v[88:91], v[224:227], v[216:219], v[88:91]
	v_mfma_f32_16x16x32_bf16 v[92:95], v[232:235], v[216:219], v[92:95]
	s_setprio 0
	s_barrier
	ds_read_b128 v[144:147], v149
	ds_read_b128 v[156:159], v149 offset:1024
	ds_read_b128 v[180:183], v149 offset:256
	ds_read_b128 v[184:187], v149 offset:1280
	s_mov_b32 m0, s41
	ds_read_b128 v[140:143], v128 offset:32768
	ds_read_b128 v[188:191], v128 offset:33792
	ds_read_b128 v[192:195], v153 offset:32768
	ds_read_b128 v[196:199], v153 offset:33792
	ds_read_b128 v[200:203], v154 offset:32768
	ds_read_b128 v[204:207], v154 offset:33792
	ds_read_b128 v[208:211], v155 offset:32768
	ds_read_b128 v[212:215], v155 offset:33792
	global_load_lds_dwordx4 v[236:237], off
	s_mov_b32 m0, vcc_lo
	v_lshl_add_u64 v[132:133], v[236:237], 0, s[8:9]
	global_load_lds_dwordx4 v[238:239], off
	v_lshl_add_u64 v[134:135], v[238:239], 0, s[8:9]
	s_waitcnt lgkmcnt(8)
	s_barrier
	s_waitcnt lgkmcnt(0)
	s_setprio 1
	s_waitcnt lgkmcnt(0)
	v_mfma_f32_16x16x32_bf16 v[124:127], v[144:147], v[140:143], v[124:127]
	v_mfma_f32_16x16x32_bf16 v[120:123], v[180:183], v[140:143], v[120:123]
	v_mfma_f32_16x16x32_bf16 v[116:119], v[144:147], v[192:195], v[116:119]
	v_mfma_f32_16x16x32_bf16 v[112:115], v[180:183], v[192:195], v[112:115]
	v_mfma_f32_16x16x32_bf16 v[108:111], v[144:147], v[200:203], v[108:111]
	v_mfma_f32_16x16x32_bf16 v[104:107], v[180:183], v[200:203], v[104:107]
	v_mfma_f32_16x16x32_bf16 v[100:103], v[144:147], v[208:211], v[100:103]
	v_mfma_f32_16x16x32_bf16 v[96:99], v[180:183], v[208:211], v[96:99]
	v_mfma_f32_16x16x32_bf16 v[124:127], v[156:159], v[188:191], v[124:127]
	v_mfma_f32_16x16x32_bf16 v[120:123], v[184:187], v[188:191], v[120:123]
	v_mfma_f32_16x16x32_bf16 v[116:119], v[156:159], v[196:199], v[116:119]
	v_mfma_f32_16x16x32_bf16 v[112:115], v[184:187], v[196:199], v[112:115]
	v_mfma_f32_16x16x32_bf16 v[108:111], v[156:159], v[204:207], v[108:111]
	v_mfma_f32_16x16x32_bf16 v[104:107], v[184:187], v[204:207], v[104:107]
	v_mfma_f32_16x16x32_bf16 v[100:103], v[156:159], v[212:215], v[100:103]
	v_mfma_f32_16x16x32_bf16 v[96:99], v[184:187], v[212:215], v[96:99]
	s_setprio 0
	s_barrier
	s_mov_b32 m0, vcc_hi
	ds_read_b128 v[216:219], v148
	ds_read_b128 v[220:223], v148 offset:1024
	ds_read_b128 v[224:227], v148 offset:256
	ds_read_b128 v[228:231], v148 offset:1280
	global_load_lds_dwordx4 v[240:241], off
	s_mov_b32 m0, s28
	v_lshl_add_u64 v[136:137], v[240:241], 0, s[8:9]
	global_load_lds_dwordx4 v[242:243], off
	v_lshl_add_u64 v[138:139], v[242:243], 0, s[8:9]
	s_barrier
	s_waitcnt lgkmcnt(0)
	s_setprio 1
	s_waitcnt lgkmcnt(0)
	v_mfma_f32_16x16x32_bf16 v[84:87], v[216:219], v[140:143], v[84:87]
	v_mfma_f32_16x16x32_bf16 v[68:71], v[224:227], v[140:143], v[68:71]
	v_mfma_f32_16x16x32_bf16 v[52:55], v[216:219], v[192:195], v[52:55]
	v_mfma_f32_16x16x32_bf16 v[48:51], v[224:227], v[192:195], v[48:51]
	v_mfma_f32_16x16x32_bf16 v[44:47], v[216:219], v[200:203], v[44:47]
	v_mfma_f32_16x16x32_bf16 v[40:43], v[224:227], v[200:203], v[40:43]
	v_mfma_f32_16x16x32_bf16 v[36:39], v[216:219], v[208:211], v[36:39]
	v_mfma_f32_16x16x32_bf16 v[32:35], v[224:227], v[208:211], v[32:35]
	v_mfma_f32_16x16x32_bf16 v[84:87], v[220:223], v[188:191], v[84:87]
	v_mfma_f32_16x16x32_bf16 v[68:71], v[228:231], v[188:191], v[68:71]
	v_mfma_f32_16x16x32_bf16 v[52:55], v[220:223], v[196:199], v[52:55]
	v_mfma_f32_16x16x32_bf16 v[48:51], v[228:231], v[196:199], v[48:51]
	v_mfma_f32_16x16x32_bf16 v[44:47], v[220:223], v[204:207], v[44:47]
	v_mfma_f32_16x16x32_bf16 v[40:43], v[228:231], v[204:207], v[40:43]
	v_mfma_f32_16x16x32_bf16 v[36:39], v[220:223], v[212:215], v[36:39]
	v_mfma_f32_16x16x32_bf16 v[32:35], v[228:231], v[212:215], v[32:35]
	s_setprio 0
	s_mov_b32 m0, s94
	s_barrier
	ds_read_b128 v[188:191], v128 offset:49152
	ds_read_b128 v[192:195], v128 offset:50176
	ds_read_b128 v[196:199], v153 offset:49152
	ds_read_b128 v[200:203], v153 offset:50176
	ds_read_b128 v[204:207], v154 offset:49152
	ds_read_b128 v[208:211], v154 offset:50176
	ds_read_b128 v[212:215], v155 offset:49152
	ds_read_b128 v[232:235], v155 offset:50176
	global_load_lds_dwordx4 v[244:245], off
	s_mov_b32 m0, s95
	v_lshl_add_u64 v[140:141], v[244:245], 0, s[8:9]
	global_load_lds_dwordx4 v[246:247], off
	v_lshl_add_u64 v[142:143], v[246:247], 0, s[8:9]
	s_barrier
; #define STAGE(P, q) do { GLDS16(q[0], (unsigned char*)(P) + wid * 1024); GLDS16(q[1], (unsigned char*)(P) + wid * 1024 + 8192); \
;     q[0] += 128; q[1] += 128; asm volatile("" : "+v"(q[0]), "+v"(q[1])); } while (0)
; #define LDA(dst, b, h) _Pragma("unroll") for (int m = 0; m < 4; ++m) _Pragma("unroll") for (int k = 0; k < 2; ++k) \
;     dst[m][k] = *(const bf16x8*)((const unsigned char*)SA(b, h) + lds_byte1(wr * 64 + m * 16 + fr, k * 32 + fq * 8))
; #define LDB(dst, b, h) _Pragma("unroll") for (int n = 0; n < 2; ++n) _Pragma("unroll") for (int k = 0; k < 2; ++k) \
;     dst[n][k] = *(const bf16x8*)((const unsigned char*)SB(b, h) + lds_byte1(wc * 32 + n * 16 + fr, k * 32 + fq * 8))
; #define MMA(ai, bj, At_, Bt_) do { __builtin_amdgcn_s_setprio(1); \
;     _Pragma("unroll") for (int m = 0; m < 4; ++m) _Pragma("unroll") for (int n = 0; n < 2; ++n) _Pragma("unroll") for (int k = 0; k < 2; ++k) \
;       acc[ai][bj][m][n] = mfma16(At_[m][k], Bt_[n][k], acc[ai][bj][m][n]); \
;     __builtin_amdgcn_s_setprio(0); } while (0)
; #define WAIT_V(n) asm volatile("s_waitcnt vmcnt(" #n ")" ::: "memory")
; #define WAIT_L(n) asm volatile("s_waitcnt lgkmcnt(" #n ")" ::: "memory")
; #define BAR __builtin_amdgcn_s_barrier()
; DEV void gemm_tile(const u16* __restrict__ A, const u16* __restrict__ Bt, u16* __restrict__ C, int N, int K,
;                    int brow, int bcol, unsigned char* smem, int epi, const GateEpi& ge) {
;     ...
;     WAIT_V(6); BAR; MMA(1, 1, At, B1); BAR;
;   }
;   { LDB(B0, 0, 0); LDA(At, 0, 0); STAGE(SA(1, 1), qA1);
;     BAR; WAIT_L(0); MMA(0, 0, At, B0); BAR;
;     LDB(B1, 0, 1); BAR; WAIT_L(0); MMA(0, 1, At, B1); BAR;
;     LDA(At, 0, 1); WAIT_V(4); BAR; WAIT_L(0); MMA(1, 0, At, B0); MMA(1, 1, At, B1); BAR; }
; DEV void phase_gemm(const u16* A, const u16* Bt, u16* C, int ntiles, int N, int K, unsigned char* smem, int epi, const GateEpi& ge) {
;     ...
;   for (int t = lb; t < ntiles; t += gridDim.x) {
	s_waitcnt lgkmcnt(0)
	s_setprio 1
	s_waitcnt lgkmcnt(0)
	v_mfma_f32_16x16x32_bf16 v[28:31], v[144:147], v[188:191], v[28:31]
	v_mfma_f32_16x16x32_bf16 v[24:27], v[180:183], v[188:191], v[24:27]
	v_mfma_f32_16x16x32_bf16 v[20:23], v[144:147], v[196:199], v[20:23]
	v_mfma_f32_16x16x32_bf16 v[16:19], v[180:183], v[196:199], v[16:19]
	v_mfma_f32_16x16x32_bf16 v[12:15], v[144:147], v[204:207], v[12:15]
	v_mfma_f32_16x16x32_bf16 v[8:11], v[180:183], v[204:207], v[8:11]
	v_mfma_f32_16x16x32_bf16 v[4:7], v[144:147], v[212:215], v[4:7]
	v_mfma_f32_16x16x32_bf16 v[0:3], v[180:183], v[212:215], v[0:3]
	v_mfma_f32_16x16x32_bf16 v[28:31], v[156:159], v[192:195], v[28:31]
	v_mfma_f32_16x16x32_bf16 v[24:27], v[184:187], v[192:195], v[24:27]
	v_mfma_f32_16x16x32_bf16 v[20:23], v[156:159], v[200:203], v[20:23]
	v_mfma_f32_16x16x32_bf16 v[16:19], v[184:187], v[200:203], v[16:19]
	v_mfma_f32_16x16x32_bf16 v[12:15], v[156:159], v[208:211], v[12:15]
	v_mfma_f32_16x16x32_bf16 v[8:11], v[184:187], v[208:211], v[8:11]
	v_mfma_f32_16x16x32_bf16 v[4:7], v[156:159], v[232:235], v[4:7]
	v_mfma_f32_16x16x32_bf16 v[0:3], v[184:187], v[232:235], v[0:3]
	s_setprio 0
	s_barrier
	s_mov_b32 m0, s62
	v_lshl_add_u64 v[144:145], v[248:249], 0, s[8:9]
	global_load_lds_dwordx4 v[248:249], off
	s_mov_b32 m0, s63
	v_lshl_add_u64 v[146:147], v[250:251], 0, s[8:9]
	global_load_lds_dwordx4 v[250:251], off
	s_waitcnt vmcnt(6)
	s_barrier
	s_setprio 1
	v_mfma_f32_16x16x32_bf16 v[56:59], v[216:219], v[188:191], v[56:59]
	v_mfma_f32_16x16x32_bf16 v[60:63], v[224:227], v[188:191], v[60:63]
	v_mfma_f32_16x16x32_bf16 v[64:67], v[216:219], v[196:199], v[64:67]
	v_mfma_f32_16x16x32_bf16 v[72:75], v[224:227], v[196:199], v[72:75]
	v_mfma_f32_16x16x32_bf16 v[76:79], v[216:219], v[204:207], v[76:79]
	v_mfma_f32_16x16x32_bf16 v[80:83], v[224:227], v[204:207], v[80:83]
	v_mfma_f32_16x16x32_bf16 v[88:91], v[216:219], v[212:215], v[88:91]
	v_mfma_f32_16x16x32_bf16 v[92:95], v[224:227], v[212:215], v[92:95]
	v_mfma_f32_16x16x32_bf16 v[56:59], v[220:223], v[192:195], v[56:59]
	v_mfma_f32_16x16x32_bf16 v[60:63], v[228:231], v[192:195], v[60:63]
	v_mfma_f32_16x16x32_bf16 v[64:67], v[220:223], v[200:203], v[64:67]
	v_mfma_f32_16x16x32_bf16 v[72:75], v[228:231], v[200:203], v[72:75]
	v_mfma_f32_16x16x32_bf16 v[76:79], v[220:223], v[208:211], v[76:79]
	v_mfma_f32_16x16x32_bf16 v[80:83], v[228:231], v[208:211], v[80:83]
	v_mfma_f32_16x16x32_bf16 v[88:91], v[220:223], v[232:235], v[88:91]
	v_mfma_f32_16x16x32_bf16 v[92:95], v[228:231], v[232:235], v[92:95]
	s_setprio 0
	s_add_i32 s57, s57, 2
	s_cmp_lt_i32 s57, s45
	s_barrier
	s_cbranch_scc1 .LBB0_634
	s_add_i32 s0, s48, s33
	s_cmp_lt_i32 s0, s43
	s_cbranch_scc1 .Lg_last
	ds_read_b128 v[156:159], v152
	ds_read_b128 v[180:183], v152 offset:1024
	ds_read_b128 v[184:187], v152 offset:256
	ds_read_b128 v[188:191], v152 offset:1280
	s_mov_b32 m0, s56
	v_add_u32_e32 v153, s53, v151
	v_add_u32_e32 v154, s54, v151
	v_add_u32_e32 v155, s55, v151
	ds_read_b128 v[192:195], v128
	ds_read_b128 v[196:199], v128 offset:1024
	ds_read_b128 v[200:203], v153
	ds_read_b128 v[204:207], v153 offset:1024
	ds_read_b128 v[208:211], v154
	ds_read_b128 v[212:215], v154 offset:1024
	ds_read_b128 v[216:219], v155
	ds_read_b128 v[220:223], v155 offset:1024
	global_load_lds_dwordx4 v[132:133], off
	s_mov_b32 m0, s52
	v_lshl_add_u64 v[236:237], v[132:133], 0, s[8:9]
	global_load_lds_dwordx4 v[134:135], off
	v_lshl_add_u64 v[238:239], v[134:135], 0, s[8:9]
	s_waitcnt lgkmcnt(8)
	s_barrier
	s_waitcnt lgkmcnt(0)
	s_setprio 1
	s_waitcnt lgkmcnt(0)
	v_mfma_f32_16x16x32_bf16 v[124:127], v[156:159], v[192:195], v[124:127]
	v_mfma_f32_16x16x32_bf16 v[120:123], v[184:187], v[192:195], v[120:123]
	v_mfma_f32_16x16x32_bf16 v[116:119], v[156:159], v[200:203], v[116:119]
	v_mfma_f32_16x16x32_bf16 v[112:115], v[184:187], v[200:203], v[112:115]
	v_mfma_f32_16x16x32_bf16 v[108:111], v[156:159], v[208:211], v[108:111]
	v_mfma_f32_16x16x32_bf16 v[104:107], v[184:187], v[208:211], v[104:107]
	v_mfma_f32_16x16x32_bf16 v[100:103], v[156:159], v[216:219], v[100:103]
	v_mfma_f32_16x16x32_bf16 v[96:99], v[184:187], v[216:219], v[96:99]
	v_mfma_f32_16x16x32_bf16 v[124:127], v[180:183], v[196:199], v[124:127]
	v_mfma_f32_16x16x32_bf16 v[120:123], v[188:191], v[196:199], v[120:123]
	v_mfma_f32_16x16x32_bf16 v[116:119], v[180:183], v[204:207], v[116:119]
	v_mfma_f32_16x16x32_bf16 v[112:115], v[188:191], v[204:207], v[112:115]
	v_mfma_f32_16x16x32_bf16 v[108:111], v[180:183], v[212:215], v[108:111]
	v_mfma_f32_16x16x32_bf16 v[104:107], v[188:191], v[212:215], v[104:107]
	v_mfma_f32_16x16x32_bf16 v[100:103], v[180:183], v[220:223], v[100:103]
	v_mfma_f32_16x16x32_bf16 v[96:99], v[188:191], v[220:223], v[96:99]
	s_setprio 0
	s_barrier
	s_mov_b32 m0, s4
	ds_read_b128 v[132:135], v150
	ds_read_b128 v[224:227], v150 offset:1024
	ds_read_b128 v[228:231], v150 offset:256
	ds_read_b128 v[232:235], v150 offset:1280
	s_mov_b32 m0, s5
	v_lshl_add_u64 v[240:241], v[136:137], 0, s[8:9]
	v_lshl_add_u64 v[242:243], v[138:139], 0, s[8:9]
	s_barrier
; #define STAGE(P, q) do { GLDS16(q[0], (unsigned char*)(P) + wid * 1024); GLDS16(q[1], (unsigned char*)(P) + wid * 1024 + 8192); \
;     q[0] += 128; q[1] += 128; asm volatile("" : "+v"(q[0]), "+v"(q[1])); } while (0)
; #define LDA(dst, b, h) _Pragma("unroll") for (int m = 0; m < 4; ++m) _Pragma("unroll") for (int k = 0; k < 2; ++k) \
;     dst[m][k] = *(const bf16x8*)((const unsigned char*)SA(b, h) + lds_byte1(wr * 64 + m * 16 + fr, k * 32 + fq * 8))
; #define LDB(dst, b, h) _Pragma("unroll") for (int n = 0; n < 2; ++n) _Pragma("unroll") for (int k = 0; k < 2; ++k) \
;     dst[n][k] = *(const bf16x8*)((const unsigned char*)SB(b, h) + lds_byte1(wc * 32 + n * 16 + fr, k * 32 + fq * 8))
; #define MMA(ai, bj, At_, Bt_) do { __builtin_amdgcn_s_setprio(1); \
;     _Pragma("unroll") for (int m = 0; m < 4; ++m) _Pragma("unroll") for (int n = 0; n < 2; ++n) _Pragma("unroll") for (int k = 0; k < 2; ++k) \
;       acc[ai][bj][m][n] = mfma16(At_[m][k], Bt_[n][k], acc[ai][bj][m][n]); \
;     __builtin_amdgcn_s_setprio(0); } while (0)
; #define WAIT_V(n) asm volatile("s_waitcnt vmcnt(" #n ")" ::: "memory")
; #define WAIT_L(n) asm volatile("s_waitcnt lgkmcnt(" #n ")" ::: "memory")
; #define BAR __builtin_amdgcn_s_barrier()
; DEV void gemm_tile(const u16* __restrict__ A, const u16* __restrict__ Bt, u16* __restrict__ C, int N, int K,
;                    int brow, int bcol, unsigned char* smem, int epi, const GateEpi& ge) {
;     ...
;   { LDB(B0, 0, 0); LDA(At, 0, 0); STAGE(SA(1, 1), qA1);
;     BAR; WAIT_L(0); MMA(0, 0, At, B0); BAR;
;     LDB(B1, 0, 1); BAR; WAIT_L(0); MMA(0, 1, At, B1); BAR;
;     LDA(At, 0, 1); WAIT_V(4); BAR; WAIT_L(0); MMA(1, 0, At, B0); MMA(1, 1, At, B1); BAR; }
;   { LDB(B0, 1, 0); LDA(At, 1, 0); WAIT_V(2); BAR; WAIT_L(0); MMA(0, 0, At, B0); BAR;
;     LDB(B1, 1, 1); WAIT_V(0); BAR; WAIT_L(0); MMA(0, 1, At, B1); BAR;
;     LDA(At, 1, 1); BAR; WAIT_L(0); MMA(1, 0, At, B0); MMA(1, 1, At, B1); BAR; }
	s_waitcnt lgkmcnt(0)
	s_setprio 1
	s_waitcnt lgkmcnt(0)
	v_mfma_f32_16x16x32_bf16 v[84:87], v[132:135], v[192:195], v[84:87]
	v_mfma_f32_16x16x32_bf16 v[68:71], v[228:231], v[192:195], v[68:71]
	v_mfma_f32_16x16x32_bf16 v[52:55], v[132:135], v[200:203], v[52:55]
	v_mfma_f32_16x16x32_bf16 v[48:51], v[228:231], v[200:203], v[48:51]
	v_mfma_f32_16x16x32_bf16 v[44:47], v[132:135], v[208:211], v[44:47]
	v_mfma_f32_16x16x32_bf16 v[40:43], v[228:231], v[208:211], v[40:43]
	v_mfma_f32_16x16x32_bf16 v[36:39], v[132:135], v[216:219], v[36:39]
	v_mfma_f32_16x16x32_bf16 v[32:35], v[228:231], v[216:219], v[32:35]
	v_mfma_f32_16x16x32_bf16 v[84:87], v[224:227], v[196:199], v[84:87]
	v_mfma_f32_16x16x32_bf16 v[68:71], v[232:235], v[196:199], v[68:71]
	v_mfma_f32_16x16x32_bf16 v[52:55], v[224:227], v[204:207], v[52:55]
	v_mfma_f32_16x16x32_bf16 v[48:51], v[232:235], v[204:207], v[48:51]
	v_mfma_f32_16x16x32_bf16 v[44:47], v[224:227], v[212:215], v[44:47]
	v_mfma_f32_16x16x32_bf16 v[40:43], v[232:235], v[212:215], v[40:43]
	v_mfma_f32_16x16x32_bf16 v[36:39], v[224:227], v[220:223], v[36:39]
	v_mfma_f32_16x16x32_bf16 v[32:35], v[232:235], v[220:223], v[32:35]
	s_setprio 0
	s_mov_b32 m0, s1
	s_barrier
	ds_read_b128 v[136:139], v128 offset:16384
	ds_read_b128 v[192:195], v128 offset:17408
	ds_read_b128 v[196:199], v153 offset:16384
	ds_read_b128 v[200:203], v153 offset:17408
	ds_read_b128 v[204:207], v154 offset:16384
	ds_read_b128 v[208:211], v154 offset:17408
	ds_read_b128 v[212:215], v155 offset:16384
	ds_read_b128 v[216:219], v155 offset:17408
	s_mov_b32 m0, s6
	v_lshl_add_u64 v[244:245], v[140:141], 0, s[8:9]
	v_lshl_add_u64 v[246:247], v[142:143], 0, s[8:9]
	s_barrier
	s_waitcnt lgkmcnt(0)
	s_setprio 1
	s_waitcnt lgkmcnt(0)
	v_mfma_f32_16x16x32_bf16 v[28:31], v[156:159], v[136:139], v[28:31]
	v_mfma_f32_16x16x32_bf16 v[24:27], v[184:187], v[136:139], v[24:27]
	v_mfma_f32_16x16x32_bf16 v[20:23], v[156:159], v[196:199], v[20:23]
	v_mfma_f32_16x16x32_bf16 v[16:19], v[184:187], v[196:199], v[16:19]
	v_mfma_f32_16x16x32_bf16 v[12:15], v[156:159], v[204:207], v[12:15]
	v_mfma_f32_16x16x32_bf16 v[8:11], v[184:187], v[204:207], v[8:11]
	v_mfma_f32_16x16x32_bf16 v[4:7], v[156:159], v[212:215], v[4:7]
	v_mfma_f32_16x16x32_bf16 v[0:3], v[184:187], v[212:215], v[0:3]
	v_mfma_f32_16x16x32_bf16 v[28:31], v[180:183], v[192:195], v[28:31]
	v_mfma_f32_16x16x32_bf16 v[24:27], v[188:191], v[192:195], v[24:27]
	v_mfma_f32_16x16x32_bf16 v[20:23], v[180:183], v[200:203], v[20:23]
	v_mfma_f32_16x16x32_bf16 v[16:19], v[188:191], v[200:203], v[16:19]
	v_mfma_f32_16x16x32_bf16 v[12:15], v[180:183], v[208:211], v[12:15]
	v_mfma_f32_16x16x32_bf16 v[8:11], v[188:191], v[208:211], v[8:11]
	v_mfma_f32_16x16x32_bf16 v[4:7], v[180:183], v[216:219], v[4:7]
	v_mfma_f32_16x16x32_bf16 v[0:3], v[188:191], v[216:219], v[0:3]
	s_setprio 0
	s_barrier
	s_mov_b32 m0, s7
	v_lshl_add_u64 v[248:249], v[144:145], 0, s[8:9]
	s_mov_b32 m0, s35
	v_lshl_add_u64 v[250:251], v[146:147], 0, s[8:9]
	s_waitcnt vmcnt(0)
	s_barrier
	s_setprio 1
	v_mfma_f32_16x16x32_bf16 v[56:59], v[132:135], v[136:139], v[56:59]
	v_mfma_f32_16x16x32_bf16 v[60:63], v[228:231], v[136:139], v[60:63]
	v_mfma_f32_16x16x32_bf16 v[64:67], v[132:135], v[196:199], v[64:67]
	v_mfma_f32_16x16x32_bf16 v[72:75], v[228:231], v[196:199], v[72:75]
	v_mfma_f32_16x16x32_bf16 v[76:79], v[132:135], v[204:207], v[76:79]
	v_mfma_f32_16x16x32_bf16 v[80:83], v[228:231], v[204:207], v[80:83]
	v_mfma_f32_16x16x32_bf16 v[88:91], v[132:135], v[212:215], v[88:91]
	v_mfma_f32_16x16x32_bf16 v[92:95], v[228:231], v[212:215], v[92:95]
	v_mfma_f32_16x16x32_bf16 v[56:59], v[224:227], v[192:195], v[56:59]
	v_mfma_f32_16x16x32_bf16 v[60:63], v[232:235], v[192:195], v[60:63]
	v_mfma_f32_16x16x32_bf16 v[64:67], v[224:227], v[200:203], v[64:67]
	v_mfma_f32_16x16x32_bf16 v[72:75], v[232:235], v[200:203], v[72:75]
	v_mfma_f32_16x16x32_bf16 v[76:79], v[224:227], v[208:211], v[76:79]
	v_mfma_f32_16x16x32_bf16 v[80:83], v[232:235], v[208:211], v[80:83]
	v_mfma_f32_16x16x32_bf16 v[88:91], v[224:227], v[216:219], v[88:91]
	v_mfma_f32_16x16x32_bf16 v[92:95], v[232:235], v[216:219], v[92:95]
	s_setprio 0
	s_barrier
	ds_read_b128 v[144:147], v149
	ds_read_b128 v[156:159], v149 offset:1024
	ds_read_b128 v[180:183], v149 offset:256
	ds_read_b128 v[184:187], v149 offset:1280
	s_mov_b32 m0, s41
	ds_read_b128 v[140:143], v128 offset:32768
	ds_read_b128 v[188:191], v128 offset:33792
	ds_read_b128 v[192:195], v153 offset:32768
	ds_read_b128 v[196:199], v153 offset:33792
	ds_read_b128 v[200:203], v154 offset:32768
	ds_read_b128 v[204:207], v154 offset:33792
	ds_read_b128 v[208:211], v155 offset:32768
	ds_read_b128 v[212:215], v155 offset:33792
	s_mov_b32 m0, vcc_lo
	v_lshl_add_u64 v[132:133], v[236:237], 0, s[8:9]
	v_lshl_add_u64 v[134:135], v[238:239], 0, s[8:9]
	s_waitcnt lgkmcnt(8)
	s_barrier
	s_waitcnt lgkmcnt(0)
	s_setprio 1
	s_waitcnt lgkmcnt(0)
	v_mfma_f32_16x16x32_bf16 v[124:127], v[144:147], v[140:143], v[124:127]
	v_mfma_f32_16x16x32_bf16 v[120:123], v[180:183], v[140:143], v[120:123]
	v_mfma_f32_16x16x32_bf16 v[116:119], v[144:147], v[192:195], v[116:119]
	v_mfma_f32_16x16x32_bf16 v[112:115], v[180:183], v[192:195], v[112:115]
	v_mfma_f32_16x16x32_bf16 v[108:111], v[144:147], v[200:203], v[108:111]
	v_mfma_f32_16x16x32_bf16 v[104:107], v[180:183], v[200:203], v[104:107]
	v_mfma_f32_16x16x32_bf16 v[100:103], v[144:147], v[208:211], v[100:103]
	v_mfma_f32_16x16x32_bf16 v[96:99], v[180:183], v[208:211], v[96:99]
	v_mfma_f32_16x16x32_bf16 v[124:127], v[156:159], v[188:191], v[124:127]
	v_mfma_f32_16x16x32_bf16 v[120:123], v[184:187], v[188:191], v[120:123]
	v_mfma_f32_16x16x32_bf16 v[116:119], v[156:159], v[196:199], v[116:119]
	v_mfma_f32_16x16x32_bf16 v[112:115], v[184:187], v[196:199], v[112:115]
	v_mfma_f32_16x16x32_bf16 v[108:111], v[156:159], v[204:207], v[108:111]
	v_mfma_f32_16x16x32_bf16 v[104:107], v[184:187], v[204:207], v[104:107]
	v_mfma_f32_16x16x32_bf16 v[100:103], v[156:159], v[212:215], v[100:103]
	v_mfma_f32_16x16x32_bf16 v[96:99], v[184:187], v[212:215], v[96:99]
	s_setprio 0
	s_barrier
; #define STAGE(P, q) do { GLDS16(q[0], (unsigned char*)(P) + wid * 1024); GLDS16(q[1], (unsigned char*)(P) + wid * 1024 + 8192); \
;     q[0] += 128; q[1] += 128; asm volatile("" : "+v"(q[0]), "+v"(q[1])); } while (0)
; #define LDA(dst, b, h) _Pragma("unroll") for (int m = 0; m < 4; ++m) _Pragma("unroll") for (int k = 0; k < 2; ++k) \
;     dst[m][k] = *(const bf16x8*)((const unsigned char*)SA(b, h) + lds_byte1(wr * 64 + m * 16 + fr, k * 32 + fq * 8))
; #define LDB(dst, b, h) _Pragma("unroll") for (int n = 0; n < 2; ++n) _Pragma("unroll") for (int k = 0; k < 2; ++k) \
;     dst[n][k] = *(const bf16x8*)((const unsigned char*)SB(b, h) + lds_byte1(wc * 32 + n * 16 + fr, k * 32 + fq * 8))
; #define MMA(ai, bj, At_, Bt_) do { __builtin_amdgcn_s_setprio(1); \
;     _Pragma("unroll") for (int m = 0; m < 4; ++m) _Pragma("unroll") for (int n = 0; n < 2; ++n) _Pragma("unroll") for (int k = 0; k < 2; ++k) \
;       acc[ai][bj][m][n] = mfma16(At_[m][k], Bt_[n][k], acc[ai][bj][m][n]); \
;     __builtin_amdgcn_s_setprio(0); } while (0)
; #define WAIT_V(n) asm volatile("s_waitcnt vmcnt(" #n ")" ::: "memory")
; #define WAIT_L(n) asm volatile("s_waitcnt lgkmcnt(" #n ")" ::: "memory")
; #define BAR __builtin_amdgcn_s_barrier()
; DEV void gemm_tile(const u16* __restrict__ A, const u16* __restrict__ Bt, u16* __restrict__ C, int N, int K,
;                    int brow, int bcol, unsigned char* smem, int epi, const GateEpi& ge) {
;     ...
;   { LDB(B0, 0, 0); LDA(At, 0, 0); STAGE(SA(1, 1), qA1);
;     BAR; WAIT_L(0); MMA(0, 0, At, B0); BAR;
;     LDB(B1, 0, 1); BAR; WAIT_L(0); MMA(0, 1, At, B1); BAR;
;     LDA(At, 0, 1); WAIT_V(4); BAR; WAIT_L(0); MMA(1, 0, At, B0); MMA(1, 1, At, B1); BAR; }
;   { LDB(B0, 1, 0); LDA(At, 1, 0); WAIT_V(2); BAR; WAIT_L(0); MMA(0, 0, At, B0); BAR;
;     LDB(B1, 1, 1); WAIT_V(0); BAR; WAIT_L(0); MMA(0, 1, At, B1); BAR;
;     LDA(At, 1, 1); BAR; WAIT_L(0); MMA(1, 0, At, B0); MMA(1, 1, At, B1); BAR; }
; DEV void phase_gemm(const u16* A, const u16* Bt, u16* C, int ntiles, int N, int K, unsigned char* smem, int epi, const GateEpi& ge) {
;     ...
;   for (int t = lb; t < ntiles; t += gridDim.x) {
;     while (rem >= nig) { rem -= nig; ++gid; }
;     const int pm = gid * 8 + (rem & 7), pn = rem >> 3;
	s_mov_b32 m0, vcc_hi
	ds_read_b128 v[216:219], v148
	ds_read_b128 v[220:223], v148 offset:1024
	ds_read_b128 v[224:227], v148 offset:256
	ds_read_b128 v[228:231], v148 offset:1280
	s_mov_b32 m0, s28
	v_lshl_add_u64 v[136:137], v[240:241], 0, s[8:9]
	v_lshl_add_u64 v[138:139], v[242:243], 0, s[8:9]
	s_barrier
	s_waitcnt lgkmcnt(0)
	s_setprio 1
	s_waitcnt lgkmcnt(0)
	v_mfma_f32_16x16x32_bf16 v[84:87], v[216:219], v[140:143], v[84:87]
	v_mfma_f32_16x16x32_bf16 v[68:71], v[224:227], v[140:143], v[68:71]
	v_mfma_f32_16x16x32_bf16 v[52:55], v[216:219], v[192:195], v[52:55]
	v_mfma_f32_16x16x32_bf16 v[48:51], v[224:227], v[192:195], v[48:51]
	v_mfma_f32_16x16x32_bf16 v[44:47], v[216:219], v[200:203], v[44:47]
	v_mfma_f32_16x16x32_bf16 v[40:43], v[224:227], v[200:203], v[40:43]
	v_mfma_f32_16x16x32_bf16 v[36:39], v[216:219], v[208:211], v[36:39]
	v_mfma_f32_16x16x32_bf16 v[32:35], v[224:227], v[208:211], v[32:35]
	v_mfma_f32_16x16x32_bf16 v[84:87], v[220:223], v[188:191], v[84:87]
	v_mfma_f32_16x16x32_bf16 v[68:71], v[228:231], v[188:191], v[68:71]
	v_mfma_f32_16x16x32_bf16 v[52:55], v[220:223], v[196:199], v[52:55]
	v_mfma_f32_16x16x32_bf16 v[48:51], v[228:231], v[196:199], v[48:51]
	v_mfma_f32_16x16x32_bf16 v[44:47], v[220:223], v[204:207], v[44:47]
	v_mfma_f32_16x16x32_bf16 v[40:43], v[228:231], v[204:207], v[40:43]
	v_mfma_f32_16x16x32_bf16 v[36:39], v[220:223], v[212:215], v[36:39]
	v_mfma_f32_16x16x32_bf16 v[32:35], v[228:231], v[212:215], v[32:35]
	s_setprio 0
	s_mov_b32 m0, s94
	s_barrier
	ds_read_b128 v[188:191], v128 offset:49152
	ds_read_b128 v[192:195], v128 offset:50176
	ds_read_b128 v[196:199], v153 offset:49152
	ds_read_b128 v[200:203], v153 offset:50176
	ds_read_b128 v[204:207], v154 offset:49152
	ds_read_b128 v[208:211], v154 offset:50176
	ds_read_b128 v[212:215], v155 offset:49152
	ds_read_b128 v[232:235], v155 offset:50176
	s_mov_b32 m0, s95
	v_lshl_add_u64 v[140:141], v[244:245], 0, s[8:9]
	v_lshl_add_u64 v[142:143], v[246:247], 0, s[8:9]
	s_barrier
	s_waitcnt lgkmcnt(0)
	s_setprio 1
	s_waitcnt lgkmcnt(0)
	v_mfma_f32_16x16x32_bf16 v[28:31], v[144:147], v[188:191], v[28:31]
	v_mfma_f32_16x16x32_bf16 v[24:27], v[180:183], v[188:191], v[24:27]
	v_mfma_f32_16x16x32_bf16 v[20:23], v[144:147], v[196:199], v[20:23]
	v_mfma_f32_16x16x32_bf16 v[16:19], v[180:183], v[196:199], v[16:19]
	v_mfma_f32_16x16x32_bf16 v[12:15], v[144:147], v[204:207], v[12:15]
	v_mfma_f32_16x16x32_bf16 v[8:11], v[180:183], v[204:207], v[8:11]
	v_mfma_f32_16x16x32_bf16 v[4:7], v[144:147], v[212:215], v[4:7]
	v_mfma_f32_16x16x32_bf16 v[0:3], v[180:183], v[212:215], v[0:3]
	v_mfma_f32_16x16x32_bf16 v[28:31], v[156:159], v[192:195], v[28:31]
	v_mfma_f32_16x16x32_bf16 v[24:27], v[184:187], v[192:195], v[24:27]
	v_mfma_f32_16x16x32_bf16 v[20:23], v[156:159], v[200:203], v[20:23]
	v_mfma_f32_16x16x32_bf16 v[16:19], v[184:187], v[200:203], v[16:19]
	v_mfma_f32_16x16x32_bf16 v[12:15], v[156:159], v[208:211], v[12:15]
	v_mfma_f32_16x16x32_bf16 v[8:11], v[184:187], v[208:211], v[8:11]
	v_mfma_f32_16x16x32_bf16 v[4:7], v[156:159], v[232:235], v[4:7]
	v_mfma_f32_16x16x32_bf16 v[0:3], v[184:187], v[232:235], v[0:3]
	s_setprio 0
	s_barrier
	s_mov_b32 m0, s62
	v_lshl_add_u64 v[144:145], v[248:249], 0, s[8:9]
	s_mov_b32 m0, s63
	v_lshl_add_u64 v[146:147], v[250:251], 0, s[8:9]
	s_waitcnt vmcnt(0)
	s_barrier
	s_setprio 1
	v_mfma_f32_16x16x32_bf16 v[56:59], v[216:219], v[188:191], v[56:59]
	v_mfma_f32_16x16x32_bf16 v[60:63], v[224:227], v[188:191], v[60:63]
	v_mfma_f32_16x16x32_bf16 v[64:67], v[216:219], v[196:199], v[64:67]
	v_mfma_f32_16x16x32_bf16 v[72:75], v[224:227], v[196:199], v[72:75]
	v_mfma_f32_16x16x32_bf16 v[76:79], v[216:219], v[204:207], v[76:79]
	v_mfma_f32_16x16x32_bf16 v[80:83], v[224:227], v[204:207], v[80:83]
	v_mfma_f32_16x16x32_bf16 v[88:91], v[216:219], v[212:215], v[88:91]
	v_mfma_f32_16x16x32_bf16 v[92:95], v[224:227], v[212:215], v[92:95]
	v_mfma_f32_16x16x32_bf16 v[56:59], v[220:223], v[192:195], v[56:59]
	v_mfma_f32_16x16x32_bf16 v[60:63], v[228:231], v[192:195], v[60:63]
	v_mfma_f32_16x16x32_bf16 v[64:67], v[220:223], v[200:203], v[64:67]
	v_mfma_f32_16x16x32_bf16 v[72:75], v[228:231], v[200:203], v[72:75]
	v_mfma_f32_16x16x32_bf16 v[76:79], v[220:223], v[208:211], v[76:79]
	v_mfma_f32_16x16x32_bf16 v[80:83], v[228:231], v[208:211], v[80:83]
	v_mfma_f32_16x16x32_bf16 v[88:91], v[220:223], v[232:235], v[88:91]
	v_mfma_f32_16x16x32_bf16 v[92:95], v[228:231], v[232:235], v[92:95]
	s_setprio 0
	s_barrier
	s_mov_b32 s63, 0
	s_branch .Lg_unstag
.Lg_last:
	ds_read_b128 v[156:159], v152
	ds_read_b128 v[180:183], v152 offset:1024
	ds_read_b128 v[184:187], v152 offset:256
	ds_read_b128 v[188:191], v152 offset:1280
	s_mov_b32 m0, s56
	v_add_u32_e32 v153, s53, v151
	v_add_u32_e32 v154, s54, v151
	v_add_u32_e32 v155, s55, v151
	ds_read_b128 v[192:195], v128
	ds_read_b128 v[196:199], v128 offset:1024
	ds_read_b128 v[200:203], v153
	ds_read_b128 v[204:207], v153 offset:1024
	ds_read_b128 v[208:211], v154
	ds_read_b128 v[212:215], v154 offset:1024
	ds_read_b128 v[216:219], v155
	ds_read_b128 v[220:223], v155 offset:1024
	global_load_lds_dwordx4 v[132:133], off
	s_mov_b32 m0, s52
	v_lshl_add_u64 v[236:237], v[132:133], 0, s[8:9]
	global_load_lds_dwordx4 v[134:135], off
	v_lshl_add_u64 v[238:239], v[134:135], 0, s[8:9]
	s_add_i32 s0, s47, s33
	s_mov_b32 s58, s46
.Lg_norm:
	s_cmp_lt_i32 s0, s42
	s_cbranch_scc1 .Lg_normdone
	s_sub_i32 s0, s0, s42
	s_add_i32 s58, s58, 1
	s_branch .Lg_norm
; #define STAGE(P, q) do { GLDS16(q[0], (unsigned char*)(P) + wid * 1024); GLDS16(q[1], (unsigned char*)(P) + wid * 1024 + 8192); \
;     q[0] += 128; q[1] += 128; asm volatile("" : "+v"(q[0]), "+v"(q[1])); } while (0)
; #define LDA(dst, b, h) _Pragma("unroll") for (int m = 0; m < 4; ++m) _Pragma("unroll") for (int k = 0; k < 2; ++k) \
;     dst[m][k] = *(const bf16x8*)((const unsigned char*)SA(b, h) + lds_byte1(wr * 64 + m * 16 + fr, k * 32 + fq * 8))
; #define LDB(dst, b, h) _Pragma("unroll") for (int n = 0; n < 2; ++n) _Pragma("unroll") for (int k = 0; k < 2; ++k) \
;     dst[n][k] = *(const bf16x8*)((const unsigned char*)SB(b, h) + lds_byte1(wc * 32 + n * 16 + fr, k * 32 + fq * 8))
; #define MMA(ai, bj, At_, Bt_) do { __builtin_amdgcn_s_setprio(1); \
;     _Pragma("unroll") for (int m = 0; m < 4; ++m) _Pragma("unroll") for (int n = 0; n < 2; ++n) _Pragma("unroll") for (int k = 0; k < 2; ++k) \
;       acc[ai][bj][m][n] = mfma16(At_[m][k], Bt_[n][k], acc[ai][bj][m][n]); \
;     __builtin_amdgcn_s_setprio(0); } while (0)
; #define WAIT_V(n) asm volatile("s_waitcnt vmcnt(" #n ")" ::: "memory")
; #define WAIT_L(n) asm volatile("s_waitcnt lgkmcnt(" #n ")" ::: "memory")
; #define BAR __builtin_amdgcn_s_barrier()
; DEV void gemm_tile(const u16* __restrict__ A, const u16* __restrict__ Bt, u16* __restrict__ C, int N, int K,
;                    int brow, int bcol, unsigned char* smem, int epi, const GateEpi& ge) {
;     ...
;   { LDB(B0, 0, 0); LDA(At, 0, 0); STAGE(SA(1, 1), qA1);
;     BAR; WAIT_L(0); MMA(0, 0, At, B0); BAR;
;     LDB(B1, 0, 1); BAR; WAIT_L(0); MMA(0, 1, At, B1); BAR;
;     LDA(At, 0, 1); WAIT_V(4); BAR; WAIT_L(0); MMA(1, 0, At, B0); MMA(1, 1, At, B1); BAR; }
;   { LDB(B0, 1, 0); LDA(At, 1, 0); WAIT_V(2); BAR; WAIT_L(0); MMA(0, 0, At, B0); BAR;
; DEV void phase_gemm(const u16* A, const u16* Bt, u16* C, int ntiles, int N, int K, unsigned char* smem, int epi, const GateEpi& ge) {
;     ...
;   const int lb = (blockIdx.x & 7) * (gridDim.x >> 3) + (blockIdx.x >> 3);
;   const int nig = 8 * nN;
;   int gid = 0, rem = lb;
;   for (int t = lb; t < ntiles; t += gridDim.x) {
;     while (rem >= nig) { rem -= nig; ++gid; }
;     const int pm = gid * 8 + (rem & 7), pn = rem >> 3;
;     gemm_tile(A, Bt, C, N, K, pm * 256, pn * 256, smem, epi, ge);
;     rem += gridDim.x;
.Lg_normdone:
	v_writelane_b32 v252, s0, 42
	v_writelane_b32 v252, s58, 43
	s_lshl_b32 s59, s0, 8
	s_and_b32 s59, s59, 0x700
	s_lshl_b32 s58, s58, 11
	s_or_b32 s59, s58, s59
	s_lshl_b32 s53, s0, 5
	s_and_b32 s53, s53, 0xffffff00
	s_sub_i32 s59, s59, s49
	s_add_i32 s59, s59, -1
	s_sub_i32 s53, s53, s92
	s_add_i32 s53, s53, -1
	s_lshl_b32 s0, s18, 1
	s_mul_hi_i32 s55, s59, s0
	s_mul_i32 s54, s59, s0
	v_lshl_add_u64 v[140:141], v[140:141], 0, s[54:55]
	v_lshl_add_u64 v[142:143], v[142:143], 0, s[54:55]
	v_lshl_add_u64 v[236:237], v[236:237], 0, s[54:55]
	v_lshl_add_u64 v[238:239], v[238:239], 0, s[54:55]
	s_mul_hi_i32 s55, s53, s0
	s_mul_i32 s54, s53, s0
	v_lshl_add_u64 v[136:137], v[136:137], 0, s[54:55]
	v_lshl_add_u64 v[138:139], v[138:139], 0, s[54:55]
	v_lshl_add_u64 v[144:145], v[144:145], 0, s[54:55]
	v_lshl_add_u64 v[146:147], v[146:147], 0, s[54:55]
	s_waitcnt lgkmcnt(8)
	s_barrier
	s_waitcnt lgkmcnt(0)
	s_setprio 1
	s_waitcnt lgkmcnt(0)
	v_mfma_f32_16x16x32_bf16 v[124:127], v[156:159], v[192:195], v[124:127]
	v_mfma_f32_16x16x32_bf16 v[120:123], v[184:187], v[192:195], v[120:123]
	v_mfma_f32_16x16x32_bf16 v[116:119], v[156:159], v[200:203], v[116:119]
	v_mfma_f32_16x16x32_bf16 v[112:115], v[184:187], v[200:203], v[112:115]
	v_mfma_f32_16x16x32_bf16 v[108:111], v[156:159], v[208:211], v[108:111]
	v_mfma_f32_16x16x32_bf16 v[104:107], v[184:187], v[208:211], v[104:107]
	v_mfma_f32_16x16x32_bf16 v[100:103], v[156:159], v[216:219], v[100:103]
	v_mfma_f32_16x16x32_bf16 v[96:99], v[184:187], v[216:219], v[96:99]
	v_mfma_f32_16x16x32_bf16 v[124:127], v[180:183], v[196:199], v[124:127]
	v_mfma_f32_16x16x32_bf16 v[120:123], v[188:191], v[196:199], v[120:123]
	v_mfma_f32_16x16x32_bf16 v[116:119], v[180:183], v[204:207], v[116:119]
	v_mfma_f32_16x16x32_bf16 v[112:115], v[188:191], v[204:207], v[112:115]
	v_mfma_f32_16x16x32_bf16 v[108:111], v[180:183], v[212:215], v[108:111]
	v_mfma_f32_16x16x32_bf16 v[104:107], v[188:191], v[212:215], v[104:107]
	v_mfma_f32_16x16x32_bf16 v[100:103], v[180:183], v[220:223], v[100:103]
	v_mfma_f32_16x16x32_bf16 v[96:99], v[188:191], v[220:223], v[96:99]
	s_setprio 0
	s_barrier
	s_mov_b32 m0, s4
	ds_read_b128 v[132:135], v150
	ds_read_b128 v[224:227], v150 offset:1024
	ds_read_b128 v[228:231], v150 offset:256
	ds_read_b128 v[232:235], v150 offset:1280
	global_load_lds_dwordx4 v[136:137], off
	s_mov_b32 m0, s5
	v_lshl_add_u64 v[240:241], v[136:137], 0, s[8:9]
	global_load_lds_dwordx4 v[138:139], off
	v_lshl_add_u64 v[242:243], v[138:139], 0, s[8:9]
	s_barrier
	s_waitcnt lgkmcnt(0)
	s_setprio 1
	s_waitcnt lgkmcnt(0)
	v_mfma_f32_16x16x32_bf16 v[84:87], v[132:135], v[192:195], v[84:87]
	v_mfma_f32_16x16x32_bf16 v[68:71], v[228:231], v[192:195], v[68:71]
	v_mfma_f32_16x16x32_bf16 v[52:55], v[132:135], v[200:203], v[52:55]
	v_mfma_f32_16x16x32_bf16 v[48:51], v[228:231], v[200:203], v[48:51]
	v_mfma_f32_16x16x32_bf16 v[44:47], v[132:135], v[208:211], v[44:47]
	v_mfma_f32_16x16x32_bf16 v[40:43], v[228:231], v[208:211], v[40:43]
	v_mfma_f32_16x16x32_bf16 v[36:39], v[132:135], v[216:219], v[36:39]
	v_mfma_f32_16x16x32_bf16 v[32:35], v[228:231], v[216:219], v[32:35]
	v_mfma_f32_16x16x32_bf16 v[84:87], v[224:227], v[196:199], v[84:87]
	v_mfma_f32_16x16x32_bf16 v[68:71], v[232:235], v[196:199], v[68:71]
	v_mfma_f32_16x16x32_bf16 v[52:55], v[224:227], v[204:207], v[52:55]
	v_mfma_f32_16x16x32_bf16 v[48:51], v[232:235], v[204:207], v[48:51]
	v_mfma_f32_16x16x32_bf16 v[44:47], v[224:227], v[212:215], v[44:47]
	v_mfma_f32_16x16x32_bf16 v[40:43], v[232:235], v[212:215], v[40:43]
	v_mfma_f32_16x16x32_bf16 v[36:39], v[224:227], v[220:223], v[36:39]
	v_mfma_f32_16x16x32_bf16 v[32:35], v[232:235], v[220:223], v[32:35]
	s_setprio 0
	s_mov_b32 m0, s1
	s_barrier
	ds_read_b128 v[136:139], v128 offset:16384
	ds_read_b128 v[192:195], v128 offset:17408
	ds_read_b128 v[196:199], v153 offset:16384
	ds_read_b128 v[200:203], v153 offset:17408
	ds_read_b128 v[204:207], v154 offset:16384
	ds_read_b128 v[208:211], v154 offset:17408
	ds_read_b128 v[212:215], v155 offset:16384
	ds_read_b128 v[216:219], v155 offset:17408
	global_load_lds_dwordx4 v[140:141], off
	s_mov_b32 m0, s6
	v_lshl_add_u64 v[244:245], v[140:141], 0, s[8:9]
	global_load_lds_dwordx4 v[142:143], off
	v_lshl_add_u64 v[246:247], v[142:143], 0, s[8:9]
	s_barrier
	s_waitcnt lgkmcnt(0)
	s_setprio 1
	s_waitcnt lgkmcnt(0)
	v_mfma_f32_16x16x32_bf16 v[28:31], v[156:159], v[136:139], v[28:31]
	v_mfma_f32_16x16x32_bf16 v[24:27], v[184:187], v[136:139], v[24:27]
	v_mfma_f32_16x16x32_bf16 v[20:23], v[156:159], v[196:199], v[20:23]
	v_mfma_f32_16x16x32_bf16 v[16:19], v[184:187], v[196:199], v[16:19]
	v_mfma_f32_16x16x32_bf16 v[12:15], v[156:159], v[204:207], v[12:15]
	v_mfma_f32_16x16x32_bf16 v[8:11], v[184:187], v[204:207], v[8:11]
	v_mfma_f32_16x16x32_bf16 v[4:7], v[156:159], v[212:215], v[4:7]
	v_mfma_f32_16x16x32_bf16 v[0:3], v[184:187], v[212:215], v[0:3]
	v_mfma_f32_16x16x32_bf16 v[28:31], v[180:183], v[192:195], v[28:31]
	v_mfma_f32_16x16x32_bf16 v[24:27], v[188:191], v[192:195], v[24:27]
	v_mfma_f32_16x16x32_bf16 v[20:23], v[180:183], v[200:203], v[20:23]
	v_mfma_f32_16x16x32_bf16 v[16:19], v[188:191], v[200:203], v[16:19]
	v_mfma_f32_16x16x32_bf16 v[12:15], v[180:183], v[208:211], v[12:15]
	v_mfma_f32_16x16x32_bf16 v[8:11], v[188:191], v[208:211], v[8:11]
	v_mfma_f32_16x16x32_bf16 v[4:7], v[180:183], v[216:219], v[4:7]
	v_mfma_f32_16x16x32_bf16 v[0:3], v[188:191], v[216:219], v[0:3]
	s_setprio 0
	s_barrier
	s_mov_b32 m0, s7
	v_lshl_add_u64 v[248:249], v[144:145], 0, s[8:9]
	global_load_lds_dwordx4 v[144:145], off
	s_mov_b32 m0, s35
	v_lshl_add_u64 v[250:251], v[146:147], 0, s[8:9]
	global_load_lds_dwordx4 v[146:147], off
	s_waitcnt vmcnt(6)
	s_barrier
; #define STAGE(P, q) do { GLDS16(q[0], (unsigned char*)(P) + wid * 1024); GLDS16(q[1], (unsigned char*)(P) + wid * 1024 + 8192); \
;     q[0] += 128; q[1] += 128; asm volatile("" : "+v"(q[0]), "+v"(q[1])); } while (0)
; #define LDA(dst, b, h) _Pragma("unroll") for (int m = 0; m < 4; ++m) _Pragma("unroll") for (int k = 0; k < 2; ++k) \
;     dst[m][k] = *(const bf16x8*)((const unsigned char*)SA(b, h) + lds_byte1(wr * 64 + m * 16 + fr, k * 32 + fq * 8))
; #define LDB(dst, b, h) _Pragma("unroll") for (int n = 0; n < 2; ++n) _Pragma("unroll") for (int k = 0; k < 2; ++k) \
;     dst[n][k] = *(const bf16x8*)((const unsigned char*)SB(b, h) + lds_byte1(wc * 32 + n * 16 + fr, k * 32 + fq * 8))
; #define MMA(ai, bj, At_, Bt_) do { __builtin_amdgcn_s_setprio(1); \
;     _Pragma("unroll") for (int m = 0; m < 4; ++m) _Pragma("unroll") for (int n = 0; n < 2; ++n) _Pragma("unroll") for (int k = 0; k < 2; ++k) \
;       acc[ai][bj][m][n] = mfma16(At_[m][k], Bt_[n][k], acc[ai][bj][m][n]); \
;     __builtin_amdgcn_s_setprio(0); } while (0)
; #define WAIT_V(n) asm volatile("s_waitcnt vmcnt(" #n ")" ::: "memory")
; #define WAIT_L(n) asm volatile("s_waitcnt lgkmcnt(" #n ")" ::: "memory")
; #define BAR __builtin_amdgcn_s_barrier()
; DEV void gemm_tile(const u16* __restrict__ A, const u16* __restrict__ Bt, u16* __restrict__ C, int N, int K,
;                    int brow, int bcol, unsigned char* smem, int epi, const GateEpi& ge) {
;     ...
;   STAGE(SB(0, 0), qB0); STAGE(SA(0, 0), qA0);
;   STAGE(SB(0, 1), qB1); STAGE(SA(0, 1), qA1);
;   if (wr == 1) BAR;
;   WAIT_V(4); BAR;
;   STAGE(SB(1, 0), qB0); STAGE(SA(1, 0), qA0); STAGE(SB(1, 1), qB1);
;   WAIT_V(6); BAR;
;     ...
;   { LDB(B0, 0, 0); LDA(At, 0, 0); STAGE(SA(1, 1), qA1);
;     BAR; WAIT_L(0); MMA(0, 0, At, B0); BAR;
;     LDB(B1, 0, 1); BAR; WAIT_L(0); MMA(0, 1, At, B1); BAR;
;     LDA(At, 0, 1); WAIT_V(4); BAR; WAIT_L(0); MMA(1, 0, At, B0); MMA(1, 1, At, B1); BAR; }
;   { LDB(B0, 1, 0); LDA(At, 1, 0); WAIT_V(2); BAR; WAIT_L(0); MMA(0, 0, At, B0); BAR;
;     LDB(B1, 1, 1); WAIT_V(0); BAR; WAIT_L(0); MMA(0, 1, At, B1); BAR;
;     LDA(At, 1, 1); BAR; WAIT_L(0); MMA(1, 0, At, B0); MMA(1, 1, At, B1); BAR; }
	s_setprio 1
	v_mfma_f32_16x16x32_bf16 v[56:59], v[132:135], v[136:139], v[56:59]
	v_mfma_f32_16x16x32_bf16 v[60:63], v[228:231], v[136:139], v[60:63]
	v_mfma_f32_16x16x32_bf16 v[64:67], v[132:135], v[196:199], v[64:67]
	v_mfma_f32_16x16x32_bf16 v[72:75], v[228:231], v[196:199], v[72:75]
	v_mfma_f32_16x16x32_bf16 v[76:79], v[132:135], v[204:207], v[76:79]
	v_mfma_f32_16x16x32_bf16 v[80:83], v[228:231], v[204:207], v[80:83]
	v_mfma_f32_16x16x32_bf16 v[88:91], v[132:135], v[212:215], v[88:91]
	v_mfma_f32_16x16x32_bf16 v[92:95], v[228:231], v[212:215], v[92:95]
	v_mfma_f32_16x16x32_bf16 v[56:59], v[224:227], v[192:195], v[56:59]
	v_mfma_f32_16x16x32_bf16 v[60:63], v[232:235], v[192:195], v[60:63]
	v_mfma_f32_16x16x32_bf16 v[64:67], v[224:227], v[200:203], v[64:67]
	v_mfma_f32_16x16x32_bf16 v[72:75], v[232:235], v[200:203], v[72:75]
	v_mfma_f32_16x16x32_bf16 v[76:79], v[224:227], v[208:211], v[76:79]
	v_mfma_f32_16x16x32_bf16 v[80:83], v[232:235], v[208:211], v[80:83]
	v_mfma_f32_16x16x32_bf16 v[88:91], v[224:227], v[216:219], v[88:91]
	v_mfma_f32_16x16x32_bf16 v[92:95], v[232:235], v[216:219], v[92:95]
	s_setprio 0
	s_barrier
	ds_read_b128 v[144:147], v149
	ds_read_b128 v[156:159], v149 offset:1024
	ds_read_b128 v[180:183], v149 offset:256
	ds_read_b128 v[184:187], v149 offset:1280
	s_mov_b32 m0, s41
	ds_read_b128 v[140:143], v128 offset:32768
	ds_read_b128 v[188:191], v128 offset:33792
	ds_read_b128 v[192:195], v153 offset:32768
	ds_read_b128 v[196:199], v153 offset:33792
	ds_read_b128 v[200:203], v154 offset:32768
	ds_read_b128 v[204:207], v154 offset:33792
	ds_read_b128 v[208:211], v155 offset:32768
	ds_read_b128 v[212:215], v155 offset:33792
	global_load_lds_dwordx4 v[236:237], off
	s_mov_b32 m0, vcc_lo
	v_lshl_add_u64 v[132:133], v[236:237], 0, s[8:9]
	global_load_lds_dwordx4 v[238:239], off
	v_lshl_add_u64 v[134:135], v[238:239], 0, s[8:9]
	s_waitcnt lgkmcnt(8)
	s_barrier
	s_waitcnt lgkmcnt(0)
	s_setprio 1
	s_waitcnt lgkmcnt(0)
	v_mfma_f32_16x16x32_bf16 v[124:127], v[144:147], v[140:143], v[124:127]
	v_mfma_f32_16x16x32_bf16 v[120:123], v[180:183], v[140:143], v[120:123]
	v_mfma_f32_16x16x32_bf16 v[116:119], v[144:147], v[192:195], v[116:119]
	v_mfma_f32_16x16x32_bf16 v[112:115], v[180:183], v[192:195], v[112:115]
	v_mfma_f32_16x16x32_bf16 v[108:111], v[144:147], v[200:203], v[108:111]
	v_mfma_f32_16x16x32_bf16 v[104:107], v[180:183], v[200:203], v[104:107]
	v_mfma_f32_16x16x32_bf16 v[100:103], v[144:147], v[208:211], v[100:103]
	v_mfma_f32_16x16x32_bf16 v[96:99], v[180:183], v[208:211], v[96:99]
	v_mfma_f32_16x16x32_bf16 v[124:127], v[156:159], v[188:191], v[124:127]
	v_mfma_f32_16x16x32_bf16 v[120:123], v[184:187], v[188:191], v[120:123]
	v_mfma_f32_16x16x32_bf16 v[116:119], v[156:159], v[196:199], v[116:119]
	v_mfma_f32_16x16x32_bf16 v[112:115], v[184:187], v[196:199], v[112:115]
	v_mfma_f32_16x16x32_bf16 v[108:111], v[156:159], v[204:207], v[108:111]
	v_mfma_f32_16x16x32_bf16 v[104:107], v[184:187], v[204:207], v[104:107]
	v_mfma_f32_16x16x32_bf16 v[100:103], v[156:159], v[212:215], v[100:103]
	v_mfma_f32_16x16x32_bf16 v[96:99], v[184:187], v[212:215], v[96:99]
	s_setprio 0
	s_barrier
	s_mov_b32 m0, vcc_hi
	ds_read_b128 v[216:219], v148
	ds_read_b128 v[220:223], v148 offset:1024
	ds_read_b128 v[224:227], v148 offset:256
	ds_read_b128 v[228:231], v148 offset:1280
	global_load_lds_dwordx4 v[240:241], off
	s_mov_b32 m0, s28
	v_lshl_add_u64 v[136:137], v[240:241], 0, s[8:9]
	global_load_lds_dwordx4 v[242:243], off
	v_lshl_add_u64 v[138:139], v[242:243], 0, s[8:9]
	s_barrier
	s_waitcnt lgkmcnt(0)
	s_setprio 1
	s_waitcnt lgkmcnt(0)
	v_mfma_f32_16x16x32_bf16 v[84:87], v[216:219], v[140:143], v[84:87]
	v_mfma_f32_16x16x32_bf16 v[68:71], v[224:227], v[140:143], v[68:71]
	v_mfma_f32_16x16x32_bf16 v[52:55], v[216:219], v[192:195], v[52:55]
	v_mfma_f32_16x16x32_bf16 v[48:51], v[224:227], v[192:195], v[48:51]
	v_mfma_f32_16x16x32_bf16 v[44:47], v[216:219], v[200:203], v[44:47]
	v_mfma_f32_16x16x32_bf16 v[40:43], v[224:227], v[200:203], v[40:43]
	v_mfma_f32_16x16x32_bf16 v[36:39], v[216:219], v[208:211], v[36:39]
	v_mfma_f32_16x16x32_bf16 v[32:35], v[224:227], v[208:211], v[32:35]
	v_mfma_f32_16x16x32_bf16 v[84:87], v[220:223], v[188:191], v[84:87]
	v_mfma_f32_16x16x32_bf16 v[68:71], v[228:231], v[188:191], v[68:71]
	v_mfma_f32_16x16x32_bf16 v[52:55], v[220:223], v[196:199], v[52:55]
	v_mfma_f32_16x16x32_bf16 v[48:51], v[228:231], v[196:199], v[48:51]
	v_mfma_f32_16x16x32_bf16 v[44:47], v[220:223], v[204:207], v[44:47]
	v_mfma_f32_16x16x32_bf16 v[40:43], v[228:231], v[204:207], v[40:43]
	v_mfma_f32_16x16x32_bf16 v[36:39], v[220:223], v[212:215], v[36:39]
	v_mfma_f32_16x16x32_bf16 v[32:35], v[228:231], v[212:215], v[32:35]
	s_setprio 0
	s_mov_b32 m0, s94
	s_barrier
	ds_read_b128 v[188:191], v128 offset:49152
	ds_read_b128 v[192:195], v128 offset:50176
	ds_read_b128 v[196:199], v153 offset:49152
	ds_read_b128 v[200:203], v153 offset:50176
	ds_read_b128 v[204:207], v154 offset:49152
	ds_read_b128 v[208:211], v154 offset:50176
	ds_read_b128 v[212:215], v155 offset:49152
	ds_read_b128 v[232:235], v155 offset:50176
	global_load_lds_dwordx4 v[244:245], off
	s_mov_b32 m0, s95
	v_lshl_add_u64 v[140:141], v[244:245], 0, s[8:9]
	global_load_lds_dwordx4 v[246:247], off
	v_lshl_add_u64 v[142:143], v[246:247], 0, s[8:9]
	s_barrier
; #define LDA(dst, b, h) _Pragma("unroll") for (int m = 0; m < 4; ++m) _Pragma("unroll") for (int k = 0; k < 2; ++k) \
;     dst[m][k] = *(const bf16x8*)((const unsigned char*)SA(b, h) + lds_byte1(wr * 64 + m * 16 + fr, k * 32 + fq * 8))
; #define LDB(dst, b, h) _Pragma("unroll") for (int n = 0; n < 2; ++n) _Pragma("unroll") for (int k = 0; k < 2; ++k) \
;     dst[n][k] = *(const bf16x8*)((const unsigned char*)SB(b, h) + lds_byte1(wc * 32 + n * 16 + fr, k * 32 + fq * 8))
; #define MMA(ai, bj, At_, Bt_) do { __builtin_amdgcn_s_setprio(1); \
;     _Pragma("unroll") for (int m = 0; m < 4; ++m) _Pragma("unroll") for (int n = 0; n < 2; ++n) _Pragma("unroll") for (int k = 0; k < 2; ++k) \
;       acc[ai][bj][m][n] = mfma16(At_[m][k], Bt_[n][k], acc[ai][bj][m][n]); \
;     __builtin_amdgcn_s_setprio(0); } while (0)
; #define WAIT_V(n) asm volatile("s_waitcnt vmcnt(" #n ")" ::: "memory")
; #define WAIT_L(n) asm volatile("s_waitcnt lgkmcnt(" #n ")" ::: "memory")
; #define BAR __builtin_amdgcn_s_barrier()
; DEV void gemm_tile(const u16* __restrict__ A, const u16* __restrict__ Bt, u16* __restrict__ C, int N, int K,
;                    int brow, int bcol, unsigned char* smem, int epi, const GateEpi& ge) {
;     ...
;   { LDB(B0, 1, 0); LDA(At, 1, 0); WAIT_V(2); BAR; WAIT_L(0); MMA(0, 0, At, B0); BAR;
;     LDB(B1, 1, 1); WAIT_V(0); BAR; WAIT_L(0); MMA(0, 1, At, B1); BAR;
;     LDA(At, 1, 1); BAR; WAIT_L(0); MMA(1, 0, At, B0); MMA(1, 1, At, B1); BAR; }
;   if (wr == 0) BAR;
;     ...
;   u16* Cw = C + (size_t)(brow + wr * 64) * N + bcol + wc * 32;
; #pragma unroll
;   for (int ai = 0; ai < 2; ++ai)
; #pragma unroll
;     for (int bj = 0; bj < 2; ++bj)
; #pragma unroll
;       for (int m = 0; m < 4; ++m)
; #pragma unroll
;         for (int n = 0; n < 2; ++n)
; #pragma unroll
;           for (int j = 0; j < 4; ++j)
;             Cw[(size_t)(ai * 128 + m * 16 + fq2 * 4 + j) * N + (bj * 128 + n * 16 + fr2)] = f2bf(acc[ai][bj][m][n][j]);
	s_waitcnt lgkmcnt(0)
	s_setprio 1
	s_waitcnt lgkmcnt(0)
	v_mfma_f32_16x16x32_bf16 v[28:31], v[144:147], v[188:191], v[28:31]
	v_mfma_f32_16x16x32_bf16 v[24:27], v[180:183], v[188:191], v[24:27]
	v_mfma_f32_16x16x32_bf16 v[20:23], v[144:147], v[196:199], v[20:23]
	v_mfma_f32_16x16x32_bf16 v[16:19], v[180:183], v[196:199], v[16:19]
	v_mfma_f32_16x16x32_bf16 v[12:15], v[144:147], v[204:207], v[12:15]
	v_mfma_f32_16x16x32_bf16 v[8:11], v[180:183], v[204:207], v[8:11]
	v_mfma_f32_16x16x32_bf16 v[4:7], v[144:147], v[212:215], v[4:7]
	v_mfma_f32_16x16x32_bf16 v[0:3], v[180:183], v[212:215], v[0:3]
	v_mfma_f32_16x16x32_bf16 v[28:31], v[156:159], v[192:195], v[28:31]
	v_mfma_f32_16x16x32_bf16 v[24:27], v[184:187], v[192:195], v[24:27]
	v_mfma_f32_16x16x32_bf16 v[20:23], v[156:159], v[200:203], v[20:23]
	v_mfma_f32_16x16x32_bf16 v[16:19], v[184:187], v[200:203], v[16:19]
	v_mfma_f32_16x16x32_bf16 v[12:15], v[156:159], v[208:211], v[12:15]
	v_mfma_f32_16x16x32_bf16 v[8:11], v[184:187], v[208:211], v[8:11]
	v_mfma_f32_16x16x32_bf16 v[4:7], v[156:159], v[232:235], v[4:7]
	v_mfma_f32_16x16x32_bf16 v[0:3], v[184:187], v[232:235], v[0:3]
	s_setprio 0
	s_barrier
	s_mov_b32 m0, s62
	v_lshl_add_u64 v[144:145], v[248:249], 0, s[8:9]
	global_load_lds_dwordx4 v[248:249], off
	s_mov_b32 m0, s63
	v_lshl_add_u64 v[146:147], v[250:251], 0, s[8:9]
	global_load_lds_dwordx4 v[250:251], off
	s_waitcnt vmcnt(6)
	s_barrier
	s_setprio 1
	v_mfma_f32_16x16x32_bf16 v[56:59], v[216:219], v[188:191], v[56:59]
	v_mfma_f32_16x16x32_bf16 v[60:63], v[224:227], v[188:191], v[60:63]
	v_mfma_f32_16x16x32_bf16 v[64:67], v[216:219], v[196:199], v[64:67]
	v_mfma_f32_16x16x32_bf16 v[72:75], v[224:227], v[196:199], v[72:75]
	v_mfma_f32_16x16x32_bf16 v[76:79], v[216:219], v[204:207], v[76:79]
	v_mfma_f32_16x16x32_bf16 v[80:83], v[224:227], v[204:207], v[80:83]
	v_mfma_f32_16x16x32_bf16 v[88:91], v[216:219], v[212:215], v[88:91]
	v_mfma_f32_16x16x32_bf16 v[92:95], v[224:227], v[212:215], v[92:95]
	v_mfma_f32_16x16x32_bf16 v[56:59], v[220:223], v[192:195], v[56:59]
	v_mfma_f32_16x16x32_bf16 v[60:63], v[228:231], v[192:195], v[60:63]
	v_mfma_f32_16x16x32_bf16 v[64:67], v[220:223], v[200:203], v[64:67]
	v_mfma_f32_16x16x32_bf16 v[72:75], v[228:231], v[200:203], v[72:75]
	v_mfma_f32_16x16x32_bf16 v[76:79], v[220:223], v[208:211], v[76:79]
	v_mfma_f32_16x16x32_bf16 v[80:83], v[228:231], v[208:211], v[80:83]
	v_mfma_f32_16x16x32_bf16 v[88:91], v[220:223], v[232:235], v[88:91]
	v_mfma_f32_16x16x32_bf16 v[92:95], v[228:231], v[232:235], v[92:95]
	s_setprio 0
	s_barrier
	s_mov_b32 s63, 1
.Lg_unstag:
	s_cmp_lg_u32 s34, 0
	s_cbranch_scc1 .Lg_epi
	s_barrier
.Lg_epi:
	v_readfirstlane_b32 s0, v160
	s_andn2_b32 s0, s0, 63
	s_andn2_b64 vcc, exec, s[2:3]
	v_or_b32_e32 v180, s0, v161
	s_nop 0
	v_bfe_u32 v181, v180, 4, 2
	v_and_b32_e32 v180, 15, v180
	s_cbranch_vccz .Lg_gate
	s_add_i32 s0, s51, s49
	s_mul_hi_u32 s1, s0, s44
	s_mul_i32 s0, s0, s44
	s_lshl_b64 s[0:1], s[0:1], 1
	s_add_u32 s0, s14, s0
	s_addc_u32 s1, s15, s1
	s_lshl_b64 s[4:5], s[92:93], 1
	s_add_u32 s0, s0, s4
	s_addc_u32 s1, s1, s5
	s_lshl_b32 s4, s50, 6
	s_add_u32 s0, s0, s4
	s_addc_u32 s1, s1, 0
	v_mul_u32_u24_e32 v153, s44, v180
	v_lshlrev_b32_e32 v153, 1, v153
	v_lshl_add_u32 v153, v181, 4, v153
	s_lshl_b32 s4, s44, 5
	s_lshl_b32 s5, s44, 7
	v_cvt_pk_bf16_f32 v184, v124, v125
	v_cvt_pk_bf16_f32 v185, v126, v127
	v_cvt_pk_bf16_f32 v186, v120, v121
	v_cvt_pk_bf16_f32 v187, v122, v123
	global_store_dwordx4 v153, v[184:187], s[0:1]
	v_cvt_pk_bf16_f32 v188, v84, v85
	v_cvt_pk_bf16_f32 v189, v86, v87
	v_cvt_pk_bf16_f32 v190, v68, v69
	v_cvt_pk_bf16_f32 v191, v70, v71
	global_store_dwordx4 v153, v[188:191], s[0:1] offset:256
	s_add_u32 s0, s0, s4
	s_addc_u32 s1, s1, 0
	v_cvt_pk_bf16_f32 v192, v116, v117
	v_cvt_pk_bf16_f32 v193, v118, v119
	v_cvt_pk_bf16_f32 v194, v112, v113
	v_cvt_pk_bf16_f32 v195, v114, v115
	global_store_dwordx4 v153, v[192:195], s[0:1]
	v_cvt_pk_bf16_f32 v196, v52, v53
	v_cvt_pk_bf16_f32 v197, v54, v55
	v_cvt_pk_bf16_f32 v198, v48, v49
	v_cvt_pk_bf16_f32 v199, v50, v51
	global_store_dwordx4 v153, v[196:199], s[0:1] offset:256
	s_add_u32 s0, s0, s4
	s_addc_u32 s1, s1, 0
	v_cvt_pk_bf16_f32 v184, v108, v109
	v_cvt_pk_bf16_f32 v185, v110, v111
	v_cvt_pk_bf16_f32 v186, v104, v105
	v_cvt_pk_bf16_f32 v187, v106, v107
	global_store_dwordx4 v153, v[184:187], s[0:1]
	v_cvt_pk_bf16_f32 v188, v44, v45
	v_cvt_pk_bf16_f32 v189, v46, v47
	v_cvt_pk_bf16_f32 v190, v40, v41
	v_cvt_pk_bf16_f32 v191, v42, v43
	global_store_dwordx4 v153, v[188:191], s[0:1] offset:256
	s_add_u32 s0, s0, s4
	s_addc_u32 s1, s1, 0
	v_cvt_pk_bf16_f32 v192, v100, v101
	v_cvt_pk_bf16_f32 v193, v102, v103
	v_cvt_pk_bf16_f32 v194, v96, v97
	v_cvt_pk_bf16_f32 v195, v98, v99
	global_store_dwordx4 v153, v[192:195], s[0:1]
	v_cvt_pk_bf16_f32 v196, v36, v37
	v_cvt_pk_bf16_f32 v197, v38, v39
	v_cvt_pk_bf16_f32 v198, v32, v33
	v_cvt_pk_bf16_f32 v199, v34, v35
	global_store_dwordx4 v153, v[196:199], s[0:1] offset:256
	s_add_u32 s0, s0, s4
	s_addc_u32 s1, s1, 0
	s_add_u32 s0, s0, s5
	s_addc_u32 s1, s1, 0
	v_cvt_pk_bf16_f32 v184, v28, v29
	v_cvt_pk_bf16_f32 v185, v30, v31
	v_cvt_pk_bf16_f32 v186, v24, v25
	v_cvt_pk_bf16_f32 v187, v26, v27
	global_store_dwordx4 v153, v[184:187], s[0:1]
	v_cvt_pk_bf16_f32 v188, v56, v57
	v_cvt_pk_bf16_f32 v189, v58, v59
	v_cvt_pk_bf16_f32 v190, v60, v61
	v_cvt_pk_bf16_f32 v191, v62, v63
	global_store_dwordx4 v153, v[188:191], s[0:1] offset:256
	s_add_u32 s0, s0, s4
	s_addc_u32 s1, s1, 0
	v_cvt_pk_bf16_f32 v192, v20, v21
	v_cvt_pk_bf16_f32 v193, v22, v23
	v_cvt_pk_bf16_f32 v194, v16, v17
	v_cvt_pk_bf16_f32 v195, v18, v19
	global_store_dwordx4 v153, v[192:195], s[0:1]
	v_cvt_pk_bf16_f32 v196, v64, v65
	v_cvt_pk_bf16_f32 v197, v66, v67
	v_cvt_pk_bf16_f32 v198, v72, v73
	v_cvt_pk_bf16_f32 v199, v74, v75
	global_store_dwordx4 v153, v[196:199], s[0:1] offset:256
	s_add_u32 s0, s0, s4
	s_addc_u32 s1, s1, 0
	v_cvt_pk_bf16_f32 v184, v12, v13
	v_cvt_pk_bf16_f32 v185, v14, v15
	v_cvt_pk_bf16_f32 v186, v8, v9
	v_cvt_pk_bf16_f32 v187, v10, v11
	global_store_dwordx4 v153, v[184:187], s[0:1]
	v_cvt_pk_bf16_f32 v188, v76, v77
	v_cvt_pk_bf16_f32 v189, v78, v79
	v_cvt_pk_bf16_f32 v190, v80, v81
	v_cvt_pk_bf16_f32 v191, v82, v83
	global_store_dwordx4 v153, v[188:191], s[0:1] offset:256
	s_add_u32 s0, s0, s4
	s_addc_u32 s1, s1, 0
	v_cvt_pk_bf16_f32 v192, v4, v5
	v_cvt_pk_bf16_f32 v193, v6, v7
	v_cvt_pk_bf16_f32 v194, v0, v1
	v_cvt_pk_bf16_f32 v195, v2, v3
	global_store_dwordx4 v153, v[192:195], s[0:1]
	v_cvt_pk_bf16_f32 v196, v88, v89
	v_cvt_pk_bf16_f32 v197, v90, v91
	v_cvt_pk_bf16_f32 v198, v92, v93
	v_cvt_pk_bf16_f32 v199, v94, v95
	global_store_dwordx4 v153, v[196:199], s[0:1] offset:256
	s_branch .Lg_post
; DEV float bf2f(u16 h) { return __uint_as_float(((uint32_t)h) << 16); }
; DEV void gemm_tile(const u16* __restrict__ A, const u16* __restrict__ Bt, u16* __restrict__ C, int N, int K,
;                    int brow, int bcol, unsigned char* smem, int epi, const GateEpi& ge) {
;     ...
;   if (epi) {
;     u16* sAt = (u16*)smem;
;     constexpr int AS = 132;
;     __syncthreads();
; #pragma unroll
;     for (int ai = 0; ai < 2; ++ai)
; #pragma unroll
;       for (int m = 0; m < 4; ++m)
; #pragma unroll
;         for (int n = 0; n < 2; ++n)
; #pragma unroll
;           for (int j = 0; j < 4; ++j)
;             sAt[(ai * 128 + wr * 64 + m * 16 + fq2 * 4 + j) * AS + wc * 32 + n * 16 + fr2] = f2bf(acc[ai][0][m][n][j]);
;     __syncthreads();
;     __builtin_amdgcn_sched_barrier(0);
;     const int pm = brow >> 8, pn = bcol >> 8;
;     float w0[2], w1[2], w2[2], bs[2];
; #pragma unroll
;     for (int n = 0; n < 2; ++n) {
;       const int cg = pn * 128 + wc * 32 + n * 16 + fr2;
;       w0[n] = ge.cw[cg]; w1[n] = ge.cw[DFF + cg]; w2[n] = ge.cw[2 * DFF + cg]; bs[n] = ge.cb[cg];
;     }
; #pragma unroll
;     for (int ai = 0; ai < 2; ++ai)
; #pragma unroll
;       for (int m = 0; m < 4; ++m) {
;         const int R0 = ai * 128 + wr * 64 + m * 16 + fq2 * 4;
; #pragma unroll
;         for (int n = 0; n < 2; ++n) {
;           const int cl = wc * 32 + n * 16 + fr2, cg = pn * 128 + cl;
;           float am2 = 0.f, am1 = 0.f;
;           if (R0 > 0) { am2 = bf2f(sAt[(R0 - 2) * AS + cl]); am1 = bf2f(sAt[(R0 - 1) * AS + cl]); }
; #pragma unroll
;           for (int j = 0; j < 4; ++j) {
;             const float a0 = acc[ai][0][m][n][j], b0 = acc[ai][1][m][n][j];
;             if (R0 > 0 || j >= 2) {
;               const float gv = gelu_tanh(bs[n] + w0[n] * am2 + w1[n] * am1 + w2[n] * a0) * b0;
.Lg_gate:
	s_lshl_b32 s0, s47, 5
	s_and_b32 s0, s0, 0xffffff00
	s_lshl_b32 s1, s50, 6
	s_add_i32 s28, s0, s1
	s_lshl_b32 s35, s28, 1
	v_readlane_b32 s56, v252, 38
	v_readlane_b32 s57, v252, 39
	v_readlane_b32 s58, v252, 40
	v_readlane_b32 s59, v252, 41
	v_lshlrev_b32_e32 v154, 5, v181
	v_add_u32_e32 v155, 0x5800, v154
	v_add_u32_e32 v156, 0xb000, v154
	s_add_u32 s56, s56, s35
	s_addc_u32 s57, s57, 0
	s_add_u32 s58, s58, s35
	s_addc_u32 s59, s59, 0
	s_nop 0
	global_load_dwordx4 v[184:187], v154, s[56:57]
	global_load_dwordx4 v[188:191], v154, s[56:57] offset:16
	global_load_dwordx4 v[192:195], v155, s[56:57]
	global_load_dwordx4 v[196:199], v155, s[56:57] offset:16
	global_load_dwordx4 v[200:203], v156, s[56:57]
	global_load_dwordx4 v[204:207], v156, s[56:57] offset:16
	global_load_dwordx4 v[208:211], v154, s[58:59]
	global_load_dwordx4 v[212:215], v154, s[58:59] offset:16
	s_add_i32 s0, s51, s49
	s_mul_hi_u32 s1, s0, s85
	s_mul_i32 s0, s0, s85
	s_add_u32 s0, s0, s28
	s_addc_u32 s1, s1, 0
	s_add_u32 s0, s80, s0
	s_addc_u32 s1, s81, s1
	s_ashr_i32 s4, s49, 8
	s_mul_i32 s4, s4, 0x5800
	s_add_i32 s4, s4, s28
	s_add_u32 s6, s22, s4
	s_addc_u32 s7, s23, 0
	s_add_u32 s54, s82, s4
	s_addc_u32 s55, s83, 0
	s_sub_u32 s54, s54, 0x26800
	s_subb_u32 s55, s55, 0
	s_add_u32 s4, s20, s4
	s_addc_u32 s5, s21, 0
	v_mul_u32_u24_e32 v153, 0x2c00, v180
	v_lshl_add_u32 v153, v181, 4, v153
	v_and_b32_e32 v157, 1, v180
	v_lshlrev_b32_e32 v157, 5, v157
	v_lshl_add_u32 v157, v181, 6, v157
	s_lshl_b32 s62, s50, 8
	s_add_i32 s62, s62, 0x20000
	v_add_u32_e32 v157, s62, v157
	s_lshl_b32 s62, s34, 10
	v_add_u32_e32 v158, s62, v157
	s_add_i32 s62, s34, 3
	s_and_b32 s62, s62, 3
	s_lshl_b32 s62, s62, 10
	v_add_u32_e32 v159, s62, v157
	s_mov_b32 s52, 0xbdd2d3e8
	s_mov_b32 s53, 0xbdd2d3e8
	s_mov_b32 s94, 1.0
	s_mov_b32 s95, 1.0
	s_mov_b32 exec_lo, 0xc000c000
	s_mov_b32 exec_hi, 0xc000c000
	ds_write_b128 v158, v[100:103]
	ds_write_b128 v158, v[96:99] offset:16
	ds_write_b128 v158, v[4:7] offset:2048
	ds_write_b128 v158, v[0:3] offset:2064
	s_mov_b64 exec, -1
	s_waitcnt lgkmcnt(0)
	s_barrier
	ds_read_b128 v[232:235], v159
	ds_read_b128 v[236:239], v159 offset:16
	s_waitcnt vmcnt(0)
	s_add_i32 s62, s34, 1
	s_lshl_b32 s62, s62, 10
	v_add_u32_e32 v156, s62, v157
	v_cmp_eq_u32_e32 vcc, 0, v180
	s_nop 1
	v_cndmask_b32_e32 v216, 0, v192, vcc
	v_cndmask_b32_e32 v217, 0, v193, vcc
	v_cndmask_b32_e32 v218, 0, v194, vcc
	v_cndmask_b32_e32 v219, 0, v195, vcc
	v_cndmask_b32_e32 v220, 0, v196, vcc
	v_cndmask_b32_e32 v221, 0, v197, vcc
	v_cndmask_b32_e32 v222, 0, v198, vcc
	v_cndmask_b32_e32 v223, 0, v199, vcc
	v_cmp_gt_u32_e32 vcc, 2, v180
	s_nop 1
	v_cndmask_b32_e32 v224, 0, v184, vcc
	v_cndmask_b32_e32 v225, 0, v185, vcc
	v_cndmask_b32_e32 v226, 0, v186, vcc
	v_cndmask_b32_e32 v227, 0, v187, vcc
	v_cndmask_b32_e32 v228, 0, v188, vcc
	v_cndmask_b32_e32 v229, 0, v189, vcc
	v_cndmask_b32_e32 v230, 0, v190, vcc
	v_cndmask_b32_e32 v231, 0, v191, vcc
	v_mov_b32_e32 v180, v163
	v_mov_b32_e32 v181, v163
	s_waitcnt lgkmcnt(0)
	v_pk_fma_f32 v[240:241], v[200:201], v[124:125], v[208:209]
	v_pk_fma_f32 v[242:243], v[202:203], v[126:127], v[210:211]
	v_pk_fma_f32 v[244:245], v[204:205], v[120:121], v[212:213]
	v_pk_fma_f32 v[246:247], v[206:207], v[122:123], v[214:215]
	v_fmac_f32_dpp v240, v124, v192 row_shr:1 row_mask:0xf bank_mask:0xf
	v_fmac_f32_dpp v241, v125, v193 row_shr:1 row_mask:0xf bank_mask:0xf
	v_fmac_f32_dpp v242, v126, v194 row_shr:1 row_mask:0xf bank_mask:0xf
	v_fmac_f32_dpp v243, v127, v195 row_shr:1 row_mask:0xf bank_mask:0xf
	v_fmac_f32_dpp v244, v120, v196 row_shr:1 row_mask:0xf bank_mask:0xf
	v_fmac_f32_dpp v245, v121, v197 row_shr:1 row_mask:0xf bank_mask:0xf
	v_fmac_f32_dpp v246, v122, v198 row_shr:1 row_mask:0xf bank_mask:0xf
	v_fmac_f32_dpp v247, v123, v199 row_shr:1 row_mask:0xf bank_mask:0xf
	v_fmac_f32_dpp v240, v232, v216 row_ror:1 row_mask:0xf bank_mask:0xf
	v_fmac_f32_dpp v241, v233, v217 row_ror:1 row_mask:0xf bank_mask:0xf
	v_fmac_f32_dpp v242, v234, v218 row_ror:1 row_mask:0xf bank_mask:0xf
	v_fmac_f32_dpp v243, v235, v219 row_ror:1 row_mask:0xf bank_mask:0xf
	v_fmac_f32_dpp v244, v236, v220 row_ror:1 row_mask:0xf bank_mask:0xf
	v_fmac_f32_dpp v245, v237, v221 row_ror:1 row_mask:0xf bank_mask:0xf
	v_fmac_f32_dpp v246, v238, v222 row_ror:1 row_mask:0xf bank_mask:0xf
	v_fmac_f32_dpp v247, v239, v223 row_ror:1 row_mask:0xf bank_mask:0xf
	v_fmac_f32_dpp v240, v124, v184 row_shr:2 row_mask:0xf bank_mask:0xf
	v_fmac_f32_dpp v241, v125, v185 row_shr:2 row_mask:0xf bank_mask:0xf
	v_fmac_f32_dpp v242, v126, v186 row_shr:2 row_mask:0xf bank_mask:0xf
	v_fmac_f32_dpp v243, v127, v187 row_shr:2 row_mask:0xf bank_mask:0xf
	v_fmac_f32_dpp v244, v120, v188 row_shr:2 row_mask:0xf bank_mask:0xf
	v_fmac_f32_dpp v245, v121, v189 row_shr:2 row_mask:0xf bank_mask:0xf
	v_fmac_f32_dpp v246, v122, v190 row_shr:2 row_mask:0xf bank_mask:0xf
	v_fmac_f32_dpp v247, v123, v191 row_shr:2 row_mask:0xf bank_mask:0xf
	v_fmac_f32_dpp v240, v232, v224 row_ror:2 row_mask:0xf bank_mask:0xf
	v_fmac_f32_dpp v241, v233, v225 row_ror:2 row_mask:0xf bank_mask:0xf
	v_fmac_f32_dpp v242, v234, v226 row_ror:2 row_mask:0xf bank_mask:0xf
	v_fmac_f32_dpp v243, v235, v227 row_ror:2 row_mask:0xf bank_mask:0xf
	v_fmac_f32_dpp v244, v236, v228 row_ror:2 row_mask:0xf bank_mask:0xf
	v_fmac_f32_dpp v245, v237, v229 row_ror:2 row_mask:0xf bank_mask:0xf
	v_fmac_f32_dpp v246, v238, v230 row_ror:2 row_mask:0xf bank_mask:0xf
	v_fmac_f32_dpp v247, v239, v231 row_ror:2 row_mask:0xf bank_mask:0xf
	ds_read_b128 v[232:235], v156
	ds_read_b128 v[236:239], v156 offset:16
	v_pk_mul_f32 v[248:249], v[240:241], v[240:241]
; DEV float bf2f(u16 h) { return __uint_as_float(((uint32_t)h) << 16); }
; DEV void gemm_tile(const u16* __restrict__ A, const u16* __restrict__ Bt, u16* __restrict__ C, int N, int K,
;                    int brow, int bcol, unsigned char* smem, int epi, const GateEpi& ge) {
;     ...
;         for (int n = 0; n < 2; ++n) {
;           const int cl = wc * 32 + n * 16 + fr2, cg = pn * 128 + cl;
;           float am2 = 0.f, am1 = 0.f;
;           if (R0 > 0) { am2 = bf2f(sAt[(R0 - 2) * AS + cl]); am1 = bf2f(sAt[(R0 - 1) * AS + cl]); }
; #pragma unroll
;           for (int j = 0; j < 4; ++j) {
;             const float a0 = acc[ai][0][m][n][j], b0 = acc[ai][1][m][n][j];
;             if (R0 > 0 || j >= 2) {
;               const float gv = gelu_tanh(bs[n] + w0[n] * am2 + w1[n] * am1 + w2[n] * a0) * b0;
;               ge.g[(size_t)(brow + R0 + j) * DFF + cg] = f2bf(gv);
;             } else {
;               ge.first_a[((size_t)pm * 2 + j) * DFF + cg] = sAt[(R0 + j) * AS + cl];
;               ge.first_b[((size_t)pm * 2 + j) * DFF + cg] = f2bf(b0);
;             }
;             if (R0 == 252 && j >= 2) ge.halo_a[((size_t)pm * 2 + (j - 2)) * DFF + cg] = sAt[(R0 + j) * AS + cl];
;             am2 = am1; am1 = a0;
	v_pk_mul_f32 v[250:251], v[242:243], v[242:243]
	v_pk_mul_f32 v[182:183], v[244:245], v[244:245]
	v_pk_mul_f32 v[154:155], v[246:247], v[246:247]
	v_pk_fma_f32 v[248:249], v[248:249], s[52:53], v[180:181]
	v_pk_fma_f32 v[250:251], v[250:251], s[52:53], v[180:181]
	v_pk_fma_f32 v[182:183], v[182:183], s[52:53], v[180:181]
	v_pk_fma_f32 v[154:155], v[154:155], s[52:53], v[180:181]
	v_pk_mul_f32 v[248:249], v[240:241], v[248:249]
	v_pk_mul_f32 v[250:251], v[242:243], v[250:251]
	v_pk_mul_f32 v[182:183], v[244:245], v[182:183]
	v_pk_mul_f32 v[154:155], v[246:247], v[154:155]
	v_exp_f32_e32 v248, v248
	v_exp_f32_e32 v249, v249
	v_exp_f32_e32 v250, v250
	v_exp_f32_e32 v251, v251
	v_exp_f32_e32 v182, v182
	v_exp_f32_e32 v183, v183
	v_exp_f32_e32 v154, v154
	v_exp_f32_e32 v155, v155
	v_pk_add_f32 v[248:249], v[248:249], s[94:95]
	v_pk_add_f32 v[250:251], v[250:251], s[94:95]
	v_pk_add_f32 v[182:183], v[182:183], s[94:95]
	v_pk_add_f32 v[154:155], v[154:155], s[94:95]
	v_rcp_f32_e32 v248, v248
	v_rcp_f32_e32 v249, v249
	v_rcp_f32_e32 v250, v250
	v_rcp_f32_e32 v251, v251
	v_rcp_f32_e32 v182, v182
	v_rcp_f32_e32 v183, v183
	v_rcp_f32_e32 v154, v154
	v_rcp_f32_e32 v155, v155
	v_pk_mul_f32 v[240:241], v[240:241], v[248:249]
	v_pk_mul_f32 v[242:243], v[242:243], v[250:251]
	v_pk_mul_f32 v[244:245], v[244:245], v[182:183]
	v_pk_mul_f32 v[246:247], v[246:247], v[154:155]
	v_pk_mul_f32 v[240:241], v[240:241], v[84:85]
	v_pk_mul_f32 v[242:243], v[242:243], v[86:87]
	v_pk_mul_f32 v[244:245], v[244:245], v[68:69]
	v_pk_mul_f32 v[246:247], v[246:247], v[70:71]
	v_cvt_pk_bf16_f32 v248, v240, v241
	v_cvt_pk_bf16_f32 v249, v242, v243
	v_cvt_pk_bf16_f32 v250, v244, v245
	v_cvt_pk_bf16_f32 v251, v246, v247
	s_cmp_lg_u32 s34, 0
	s_cbranch_scc1 .Lgate_plain00
	s_mov_b32 exec_lo, 0x30003
	s_mov_b32 exec_hi, 0x30003
	v_cvt_pk_bf16_f32 v240, v124, v125
	v_cvt_pk_bf16_f32 v241, v126, v127
	v_cvt_pk_bf16_f32 v242, v120, v121
	v_cvt_pk_bf16_f32 v243, v122, v123
	v_cvt_pk_bf16_f32 v244, v84, v85
	v_cvt_pk_bf16_f32 v245, v86, v87
	v_cvt_pk_bf16_f32 v246, v68, v69
	v_cvt_pk_bf16_f32 v247, v70, v71
	global_store_dwordx4 v153, v[240:243], s[4:5]
	global_store_dwordx4 v153, v[244:247], s[6:7]
	s_not_b64 exec, exec
	global_store_dwordx4 v153, v[248:251], s[0:1]
	s_mov_b64 exec, -1
	s_branch .Lgate_done00
.Lgate_plain00:
	global_store_dwordx4 v153, v[248:251], s[0:1]
.Lgate_done00:
	s_add_u32 s0, s0, 0x2c000
	s_addc_u32 s1, s1, 0
	v_pk_fma_f32 v[240:241], v[200:201], v[116:117], v[208:209]
	v_pk_fma_f32 v[242:243], v[202:203], v[118:119], v[210:211]
	v_pk_fma_f32 v[244:245], v[204:205], v[112:113], v[212:213]
	v_pk_fma_f32 v[246:247], v[206:207], v[114:115], v[214:215]
	v_fmac_f32_dpp v240, v116, v192 row_shr:1 row_mask:0xf bank_mask:0xf
	v_fmac_f32_dpp v241, v117, v193 row_shr:1 row_mask:0xf bank_mask:0xf
	v_fmac_f32_dpp v242, v118, v194 row_shr:1 row_mask:0xf bank_mask:0xf
	v_fmac_f32_dpp v243, v119, v195 row_shr:1 row_mask:0xf bank_mask:0xf
	v_fmac_f32_dpp v244, v112, v196 row_shr:1 row_mask:0xf bank_mask:0xf
	v_fmac_f32_dpp v245, v113, v197 row_shr:1 row_mask:0xf bank_mask:0xf
	v_fmac_f32_dpp v246, v114, v198 row_shr:1 row_mask:0xf bank_mask:0xf
	v_fmac_f32_dpp v247, v115, v199 row_shr:1 row_mask:0xf bank_mask:0xf
	v_fmac_f32_dpp v240, v124, v216 row_ror:1 row_mask:0xf bank_mask:0xf
	v_fmac_f32_dpp v241, v125, v217 row_ror:1 row_mask:0xf bank_mask:0xf
	v_fmac_f32_dpp v242, v126, v218 row_ror:1 row_mask:0xf bank_mask:0xf
	v_fmac_f32_dpp v243, v127, v219 row_ror:1 row_mask:0xf bank_mask:0xf
	v_fmac_f32_dpp v244, v120, v220 row_ror:1 row_mask:0xf bank_mask:0xf
	v_fmac_f32_dpp v245, v121, v221 row_ror:1 row_mask:0xf bank_mask:0xf
	v_fmac_f32_dpp v246, v122, v222 row_ror:1 row_mask:0xf bank_mask:0xf
	v_fmac_f32_dpp v247, v123, v223 row_ror:1 row_mask:0xf bank_mask:0xf
	v_fmac_f32_dpp v240, v116, v184 row_shr:2 row_mask:0xf bank_mask:0xf
	v_fmac_f32_dpp v241, v117, v185 row_shr:2 row_mask:0xf bank_mask:0xf
	v_fmac_f32_dpp v242, v118, v186 row_shr:2 row_mask:0xf bank_mask:0xf
	v_fmac_f32_dpp v243, v119, v187 row_shr:2 row_mask:0xf bank_mask:0xf
	v_fmac_f32_dpp v244, v112, v188 row_shr:2 row_mask:0xf bank_mask:0xf
	v_fmac_f32_dpp v245, v113, v189 row_shr:2 row_mask:0xf bank_mask:0xf
	v_fmac_f32_dpp v246, v114, v190 row_shr:2 row_mask:0xf bank_mask:0xf
	v_fmac_f32_dpp v247, v115, v191 row_shr:2 row_mask:0xf bank_mask:0xf
	v_fmac_f32_dpp v240, v124, v224 row_ror:2 row_mask:0xf bank_mask:0xf
	v_fmac_f32_dpp v241, v125, v225 row_ror:2 row_mask:0xf bank_mask:0xf
	v_fmac_f32_dpp v242, v126, v226 row_ror:2 row_mask:0xf bank_mask:0xf
	v_fmac_f32_dpp v243, v127, v227 row_ror:2 row_mask:0xf bank_mask:0xf
	v_fmac_f32_dpp v244, v120, v228 row_ror:2 row_mask:0xf bank_mask:0xf
	v_fmac_f32_dpp v245, v121, v229 row_ror:2 row_mask:0xf bank_mask:0xf
	v_fmac_f32_dpp v246, v122, v230 row_ror:2 row_mask:0xf bank_mask:0xf
	v_fmac_f32_dpp v247, v123, v231 row_ror:2 row_mask:0xf bank_mask:0xf
	v_pk_mul_f32 v[248:249], v[240:241], v[240:241]
	v_pk_mul_f32 v[250:251], v[242:243], v[242:243]
	v_pk_mul_f32 v[182:183], v[244:245], v[244:245]
	v_pk_mul_f32 v[154:155], v[246:247], v[246:247]
	v_pk_fma_f32 v[248:249], v[248:249], s[52:53], v[180:181]
	v_pk_fma_f32 v[250:251], v[250:251], s[52:53], v[180:181]
	v_pk_fma_f32 v[182:183], v[182:183], s[52:53], v[180:181]
	v_pk_fma_f32 v[154:155], v[154:155], s[52:53], v[180:181]
	v_pk_mul_f32 v[248:249], v[240:241], v[248:249]
	v_pk_mul_f32 v[250:251], v[242:243], v[250:251]
	v_pk_mul_f32 v[182:183], v[244:245], v[182:183]
	v_pk_mul_f32 v[154:155], v[246:247], v[154:155]
	v_exp_f32_e32 v248, v248
	v_exp_f32_e32 v249, v249
	v_exp_f32_e32 v250, v250
	v_exp_f32_e32 v251, v251
; DEV float bf2f(u16 h) { return __uint_as_float(((uint32_t)h) << 16); }
; DEV void gemm_tile(const u16* __restrict__ A, const u16* __restrict__ Bt, u16* __restrict__ C, int N, int K,
;                    int brow, int bcol, unsigned char* smem, int epi, const GateEpi& ge) {
;     ...
;         for (int n = 0; n < 2; ++n) {
;           const int cl = wc * 32 + n * 16 + fr2, cg = pn * 128 + cl;
;           float am2 = 0.f, am1 = 0.f;
;           if (R0 > 0) { am2 = bf2f(sAt[(R0 - 2) * AS + cl]); am1 = bf2f(sAt[(R0 - 1) * AS + cl]); }
; #pragma unroll
;           for (int j = 0; j < 4; ++j) {
;             const float a0 = acc[ai][0][m][n][j], b0 = acc[ai][1][m][n][j];
;             if (R0 > 0 || j >= 2) {
;               const float gv = gelu_tanh(bs[n] + w0[n] * am2 + w1[n] * am1 + w2[n] * a0) * b0;
;               ge.g[(size_t)(brow + R0 + j) * DFF + cg] = f2bf(gv);
;             } else {
;               ge.first_a[((size_t)pm * 2 + j) * DFF + cg] = sAt[(R0 + j) * AS + cl];
;               ge.first_b[((size_t)pm * 2 + j) * DFF + cg] = f2bf(b0);
;             }
;             if (R0 == 252 && j >= 2) ge.halo_a[((size_t)pm * 2 + (j - 2)) * DFF + cg] = sAt[(R0 + j) * AS + cl];
;             am2 = am1; am1 = a0;
	v_exp_f32_e32 v182, v182
	v_exp_f32_e32 v183, v183
	v_exp_f32_e32 v154, v154
	v_exp_f32_e32 v155, v155
	v_pk_add_f32 v[248:249], v[248:249], s[94:95]
	v_pk_add_f32 v[250:251], v[250:251], s[94:95]
	v_pk_add_f32 v[182:183], v[182:183], s[94:95]
	v_pk_add_f32 v[154:155], v[154:155], s[94:95]
	v_rcp_f32_e32 v248, v248
	v_rcp_f32_e32 v249, v249
	v_rcp_f32_e32 v250, v250
	v_rcp_f32_e32 v251, v251
	v_rcp_f32_e32 v182, v182
	v_rcp_f32_e32 v183, v183
	v_rcp_f32_e32 v154, v154
	v_rcp_f32_e32 v155, v155
	v_pk_mul_f32 v[240:241], v[240:241], v[248:249]
	v_pk_mul_f32 v[242:243], v[242:243], v[250:251]
	v_pk_mul_f32 v[244:245], v[244:245], v[182:183]
	v_pk_mul_f32 v[246:247], v[246:247], v[154:155]
	v_pk_mul_f32 v[240:241], v[240:241], v[52:53]
	v_pk_mul_f32 v[242:243], v[242:243], v[54:55]
	v_pk_mul_f32 v[244:245], v[244:245], v[48:49]
	v_pk_mul_f32 v[246:247], v[246:247], v[50:51]
	v_cvt_pk_bf16_f32 v248, v240, v241
	v_cvt_pk_bf16_f32 v249, v242, v243
	v_cvt_pk_bf16_f32 v250, v244, v245
	v_cvt_pk_bf16_f32 v251, v246, v247
	global_store_dwordx4 v153, v[248:251], s[0:1]
	s_add_u32 s0, s0, 0x2c000
	s_addc_u32 s1, s1, 0
	v_pk_fma_f32 v[240:241], v[200:201], v[108:109], v[208:209]
	v_pk_fma_f32 v[242:243], v[202:203], v[110:111], v[210:211]
	v_pk_fma_f32 v[244:245], v[204:205], v[104:105], v[212:213]
	v_pk_fma_f32 v[246:247], v[206:207], v[106:107], v[214:215]
	v_fmac_f32_dpp v240, v108, v192 row_shr:1 row_mask:0xf bank_mask:0xf
	v_fmac_f32_dpp v241, v109, v193 row_shr:1 row_mask:0xf bank_mask:0xf
	v_fmac_f32_dpp v242, v110, v194 row_shr:1 row_mask:0xf bank_mask:0xf
	v_fmac_f32_dpp v243, v111, v195 row_shr:1 row_mask:0xf bank_mask:0xf
	v_fmac_f32_dpp v244, v104, v196 row_shr:1 row_mask:0xf bank_mask:0xf
	v_fmac_f32_dpp v245, v105, v197 row_shr:1 row_mask:0xf bank_mask:0xf
	v_fmac_f32_dpp v246, v106, v198 row_shr:1 row_mask:0xf bank_mask:0xf
	v_fmac_f32_dpp v247, v107, v199 row_shr:1 row_mask:0xf bank_mask:0xf
	v_fmac_f32_dpp v240, v116, v216 row_ror:1 row_mask:0xf bank_mask:0xf
	v_fmac_f32_dpp v241, v117, v217 row_ror:1 row_mask:0xf bank_mask:0xf
	v_fmac_f32_dpp v242, v118, v218 row_ror:1 row_mask:0xf bank_mask:0xf
	v_fmac_f32_dpp v243, v119, v219 row_ror:1 row_mask:0xf bank_mask:0xf
	v_fmac_f32_dpp v244, v112, v220 row_ror:1 row_mask:0xf bank_mask:0xf
	v_fmac_f32_dpp v245, v113, v221 row_ror:1 row_mask:0xf bank_mask:0xf
	v_fmac_f32_dpp v246, v114, v222 row_ror:1 row_mask:0xf bank_mask:0xf
	v_fmac_f32_dpp v247, v115, v223 row_ror:1 row_mask:0xf bank_mask:0xf
	v_fmac_f32_dpp v240, v108, v184 row_shr:2 row_mask:0xf bank_mask:0xf
	v_fmac_f32_dpp v241, v109, v185 row_shr:2 row_mask:0xf bank_mask:0xf
	v_fmac_f32_dpp v242, v110, v186 row_shr:2 row_mask:0xf bank_mask:0xf
	v_fmac_f32_dpp v243, v111, v187 row_shr:2 row_mask:0xf bank_mask:0xf
	v_fmac_f32_dpp v244, v104, v188 row_shr:2 row_mask:0xf bank_mask:0xf
	v_fmac_f32_dpp v245, v105, v189 row_shr:2 row_mask:0xf bank_mask:0xf
	v_fmac_f32_dpp v246, v106, v190 row_shr:2 row_mask:0xf bank_mask:0xf
	v_fmac_f32_dpp v247, v107, v191 row_shr:2 row_mask:0xf bank_mask:0xf
	v_fmac_f32_dpp v240, v116, v224 row_ror:2 row_mask:0xf bank_mask:0xf
	v_fmac_f32_dpp v241, v117, v225 row_ror:2 row_mask:0xf bank_mask:0xf
	v_fmac_f32_dpp v242, v118, v226 row_ror:2 row_mask:0xf bank_mask:0xf
	v_fmac_f32_dpp v243, v119, v227 row_ror:2 row_mask:0xf bank_mask:0xf
	v_fmac_f32_dpp v244, v112, v228 row_ror:2 row_mask:0xf bank_mask:0xf
	v_fmac_f32_dpp v245, v113, v229 row_ror:2 row_mask:0xf bank_mask:0xf
	v_fmac_f32_dpp v246, v114, v230 row_ror:2 row_mask:0xf bank_mask:0xf
	v_fmac_f32_dpp v247, v115, v231 row_ror:2 row_mask:0xf bank_mask:0xf
	v_pk_mul_f32 v[248:249], v[240:241], v[240:241]
	v_pk_mul_f32 v[250:251], v[242:243], v[242:243]
	v_pk_mul_f32 v[182:183], v[244:245], v[244:245]
	v_pk_mul_f32 v[154:155], v[246:247], v[246:247]
	v_pk_fma_f32 v[248:249], v[248:249], s[52:53], v[180:181]
	v_pk_fma_f32 v[250:251], v[250:251], s[52:53], v[180:181]
	v_pk_fma_f32 v[182:183], v[182:183], s[52:53], v[180:181]
	v_pk_fma_f32 v[154:155], v[154:155], s[52:53], v[180:181]
	v_pk_mul_f32 v[248:249], v[240:241], v[248:249]
	v_pk_mul_f32 v[250:251], v[242:243], v[250:251]
	v_pk_mul_f32 v[182:183], v[244:245], v[182:183]
	v_pk_mul_f32 v[154:155], v[246:247], v[154:155]
	v_exp_f32_e32 v248, v248
	v_exp_f32_e32 v249, v249
	v_exp_f32_e32 v250, v250
	v_exp_f32_e32 v251, v251
	v_exp_f32_e32 v182, v182
	v_exp_f32_e32 v183, v183
	v_exp_f32_e32 v154, v154
	v_exp_f32_e32 v155, v155
	v_pk_add_f32 v[248:249], v[248:249], s[94:95]
	v_pk_add_f32 v[250:251], v[250:251], s[94:95]
	v_pk_add_f32 v[182:183], v[182:183], s[94:95]
	v_pk_add_f32 v[154:155], v[154:155], s[94:95]
	v_rcp_f32_e32 v248, v248
	v_rcp_f32_e32 v249, v249
	v_rcp_f32_e32 v250, v250
	v_rcp_f32_e32 v251, v251
	v_rcp_f32_e32 v182, v182
	v_rcp_f32_e32 v183, v183
	v_rcp_f32_e32 v154, v154
	v_rcp_f32_e32 v155, v155
	v_pk_mul_f32 v[240:241], v[240:241], v[248:249]
	v_pk_mul_f32 v[242:243], v[242:243], v[250:251]
	v_pk_mul_f32 v[244:245], v[244:245], v[182:183]
	v_pk_mul_f32 v[246:247], v[246:247], v[154:155]
	v_pk_mul_f32 v[240:241], v[240:241], v[44:45]
	v_pk_mul_f32 v[242:243], v[242:243], v[46:47]
	v_pk_mul_f32 v[244:245], v[244:245], v[40:41]
	v_pk_mul_f32 v[246:247], v[246:247], v[42:43]
	v_cvt_pk_bf16_f32 v248, v240, v241
	v_cvt_pk_bf16_f32 v249, v242, v243
	v_cvt_pk_bf16_f32 v250, v244, v245
	v_cvt_pk_bf16_f32 v251, v246, v247
	global_store_dwordx4 v153, v[248:251], s[0:1]
	s_add_u32 s0, s0, 0x2c000
	s_addc_u32 s1, s1, 0
	v_pk_fma_f32 v[240:241], v[200:201], v[100:101], v[208:209]
	v_pk_fma_f32 v[242:243], v[202:203], v[102:103], v[210:211]
	v_pk_fma_f32 v[244:245], v[204:205], v[96:97], v[212:213]
; DEV float bf2f(u16 h) { return __uint_as_float(((uint32_t)h) << 16); }
; DEV void gemm_tile(const u16* __restrict__ A, const u16* __restrict__ Bt, u16* __restrict__ C, int N, int K,
;                    int brow, int bcol, unsigned char* smem, int epi, const GateEpi& ge) {
;     ...
;         for (int n = 0; n < 2; ++n) {
;           const int cl = wc * 32 + n * 16 + fr2, cg = pn * 128 + cl;
;           float am2 = 0.f, am1 = 0.f;
;           if (R0 > 0) { am2 = bf2f(sAt[(R0 - 2) * AS + cl]); am1 = bf2f(sAt[(R0 - 1) * AS + cl]); }
; #pragma unroll
;           for (int j = 0; j < 4; ++j) {
;             const float a0 = acc[ai][0][m][n][j], b0 = acc[ai][1][m][n][j];
;             if (R0 > 0 || j >= 2) {
;               const float gv = gelu_tanh(bs[n] + w0[n] * am2 + w1[n] * am1 + w2[n] * a0) * b0;
;               ge.g[(size_t)(brow + R0 + j) * DFF + cg] = f2bf(gv);
;             } else {
;               ge.first_a[((size_t)pm * 2 + j) * DFF + cg] = sAt[(R0 + j) * AS + cl];
;               ge.first_b[((size_t)pm * 2 + j) * DFF + cg] = f2bf(b0);
;             }
;             if (R0 == 252 && j >= 2) ge.halo_a[((size_t)pm * 2 + (j - 2)) * DFF + cg] = sAt[(R0 + j) * AS + cl];
;             am2 = am1; am1 = a0;
	v_pk_fma_f32 v[246:247], v[206:207], v[98:99], v[214:215]
	v_fmac_f32_dpp v240, v100, v192 row_shr:1 row_mask:0xf bank_mask:0xf
	v_fmac_f32_dpp v241, v101, v193 row_shr:1 row_mask:0xf bank_mask:0xf
	v_fmac_f32_dpp v242, v102, v194 row_shr:1 row_mask:0xf bank_mask:0xf
	v_fmac_f32_dpp v243, v103, v195 row_shr:1 row_mask:0xf bank_mask:0xf
	v_fmac_f32_dpp v244, v96, v196 row_shr:1 row_mask:0xf bank_mask:0xf
	v_fmac_f32_dpp v245, v97, v197 row_shr:1 row_mask:0xf bank_mask:0xf
	v_fmac_f32_dpp v246, v98, v198 row_shr:1 row_mask:0xf bank_mask:0xf
	v_fmac_f32_dpp v247, v99, v199 row_shr:1 row_mask:0xf bank_mask:0xf
	v_fmac_f32_dpp v240, v108, v216 row_ror:1 row_mask:0xf bank_mask:0xf
	v_fmac_f32_dpp v241, v109, v217 row_ror:1 row_mask:0xf bank_mask:0xf
	v_fmac_f32_dpp v242, v110, v218 row_ror:1 row_mask:0xf bank_mask:0xf
	v_fmac_f32_dpp v243, v111, v219 row_ror:1 row_mask:0xf bank_mask:0xf
	v_fmac_f32_dpp v244, v104, v220 row_ror:1 row_mask:0xf bank_mask:0xf
	v_fmac_f32_dpp v245, v105, v221 row_ror:1 row_mask:0xf bank_mask:0xf
	v_fmac_f32_dpp v246, v106, v222 row_ror:1 row_mask:0xf bank_mask:0xf
	v_fmac_f32_dpp v247, v107, v223 row_ror:1 row_mask:0xf bank_mask:0xf
	v_fmac_f32_dpp v240, v100, v184 row_shr:2 row_mask:0xf bank_mask:0xf
	v_fmac_f32_dpp v241, v101, v185 row_shr:2 row_mask:0xf bank_mask:0xf
	v_fmac_f32_dpp v242, v102, v186 row_shr:2 row_mask:0xf bank_mask:0xf
	v_fmac_f32_dpp v243, v103, v187 row_shr:2 row_mask:0xf bank_mask:0xf
	v_fmac_f32_dpp v244, v96, v188 row_shr:2 row_mask:0xf bank_mask:0xf
	v_fmac_f32_dpp v245, v97, v189 row_shr:2 row_mask:0xf bank_mask:0xf
	v_fmac_f32_dpp v246, v98, v190 row_shr:2 row_mask:0xf bank_mask:0xf
	v_fmac_f32_dpp v247, v99, v191 row_shr:2 row_mask:0xf bank_mask:0xf
	v_fmac_f32_dpp v240, v108, v224 row_ror:2 row_mask:0xf bank_mask:0xf
	v_fmac_f32_dpp v241, v109, v225 row_ror:2 row_mask:0xf bank_mask:0xf
	v_fmac_f32_dpp v242, v110, v226 row_ror:2 row_mask:0xf bank_mask:0xf
	v_fmac_f32_dpp v243, v111, v227 row_ror:2 row_mask:0xf bank_mask:0xf
	v_fmac_f32_dpp v244, v104, v228 row_ror:2 row_mask:0xf bank_mask:0xf
	v_fmac_f32_dpp v245, v105, v229 row_ror:2 row_mask:0xf bank_mask:0xf
	v_fmac_f32_dpp v246, v106, v230 row_ror:2 row_mask:0xf bank_mask:0xf
	v_fmac_f32_dpp v247, v107, v231 row_ror:2 row_mask:0xf bank_mask:0xf
	v_pk_mul_f32 v[248:249], v[240:241], v[240:241]
	v_pk_mul_f32 v[250:251], v[242:243], v[242:243]
	v_pk_mul_f32 v[182:183], v[244:245], v[244:245]
	v_pk_mul_f32 v[154:155], v[246:247], v[246:247]
	v_pk_fma_f32 v[248:249], v[248:249], s[52:53], v[180:181]
	v_pk_fma_f32 v[250:251], v[250:251], s[52:53], v[180:181]
	v_pk_fma_f32 v[182:183], v[182:183], s[52:53], v[180:181]
	v_pk_fma_f32 v[154:155], v[154:155], s[52:53], v[180:181]
	v_pk_mul_f32 v[248:249], v[240:241], v[248:249]
	v_pk_mul_f32 v[250:251], v[242:243], v[250:251]
	v_pk_mul_f32 v[182:183], v[244:245], v[182:183]
	v_pk_mul_f32 v[154:155], v[246:247], v[154:155]
	v_exp_f32_e32 v248, v248
	v_exp_f32_e32 v249, v249
	v_exp_f32_e32 v250, v250
	v_exp_f32_e32 v251, v251
	v_exp_f32_e32 v182, v182
	v_exp_f32_e32 v183, v183
	v_exp_f32_e32 v154, v154
	v_exp_f32_e32 v155, v155
	v_pk_add_f32 v[248:249], v[248:249], s[94:95]
	v_pk_add_f32 v[250:251], v[250:251], s[94:95]
	v_pk_add_f32 v[182:183], v[182:183], s[94:95]
	v_pk_add_f32 v[154:155], v[154:155], s[94:95]
	v_rcp_f32_e32 v248, v248
	v_rcp_f32_e32 v249, v249
	v_rcp_f32_e32 v250, v250
	v_rcp_f32_e32 v251, v251
	v_rcp_f32_e32 v182, v182
	v_rcp_f32_e32 v183, v183
	v_rcp_f32_e32 v154, v154
	v_rcp_f32_e32 v155, v155
	v_pk_mul_f32 v[240:241], v[240:241], v[248:249]
	v_pk_mul_f32 v[242:243], v[242:243], v[250:251]
	v_pk_mul_f32 v[244:245], v[244:245], v[182:183]
	v_pk_mul_f32 v[246:247], v[246:247], v[154:155]
	v_pk_mul_f32 v[240:241], v[240:241], v[36:37]
	v_pk_mul_f32 v[242:243], v[242:243], v[38:39]
	v_pk_mul_f32 v[244:245], v[244:245], v[32:33]
	v_pk_mul_f32 v[246:247], v[246:247], v[34:35]
	v_cvt_pk_bf16_f32 v248, v240, v241
	v_cvt_pk_bf16_f32 v249, v242, v243
	v_cvt_pk_bf16_f32 v250, v244, v245
	v_cvt_pk_bf16_f32 v251, v246, v247
	global_store_dwordx4 v153, v[248:251], s[0:1]
	s_add_u32 s0, s0, 0xdc000
	s_addc_u32 s1, s1, 0
	s_waitcnt lgkmcnt(0)
	v_pk_fma_f32 v[240:241], v[200:201], v[28:29], v[208:209]
	v_pk_fma_f32 v[242:243], v[202:203], v[30:31], v[210:211]
	v_pk_fma_f32 v[244:245], v[204:205], v[24:25], v[212:213]
	v_pk_fma_f32 v[246:247], v[206:207], v[26:27], v[214:215]
	v_fmac_f32_dpp v240, v28, v192 row_shr:1 row_mask:0xf bank_mask:0xf
	v_fmac_f32_dpp v241, v29, v193 row_shr:1 row_mask:0xf bank_mask:0xf
	v_fmac_f32_dpp v242, v30, v194 row_shr:1 row_mask:0xf bank_mask:0xf
	v_fmac_f32_dpp v243, v31, v195 row_shr:1 row_mask:0xf bank_mask:0xf
	v_fmac_f32_dpp v244, v24, v196 row_shr:1 row_mask:0xf bank_mask:0xf
	v_fmac_f32_dpp v245, v25, v197 row_shr:1 row_mask:0xf bank_mask:0xf
	v_fmac_f32_dpp v246, v26, v198 row_shr:1 row_mask:0xf bank_mask:0xf
	v_fmac_f32_dpp v247, v27, v199 row_shr:1 row_mask:0xf bank_mask:0xf
	v_fmac_f32_dpp v240, v232, v216 row_ror:1 row_mask:0xf bank_mask:0xf
	v_fmac_f32_dpp v241, v233, v217 row_ror:1 row_mask:0xf bank_mask:0xf
	v_fmac_f32_dpp v242, v234, v218 row_ror:1 row_mask:0xf bank_mask:0xf
	v_fmac_f32_dpp v243, v235, v219 row_ror:1 row_mask:0xf bank_mask:0xf
	v_fmac_f32_dpp v244, v236, v220 row_ror:1 row_mask:0xf bank_mask:0xf
	v_fmac_f32_dpp v245, v237, v221 row_ror:1 row_mask:0xf bank_mask:0xf
	v_fmac_f32_dpp v246, v238, v222 row_ror:1 row_mask:0xf bank_mask:0xf
	v_fmac_f32_dpp v247, v239, v223 row_ror:1 row_mask:0xf bank_mask:0xf
	v_fmac_f32_dpp v240, v28, v184 row_shr:2 row_mask:0xf bank_mask:0xf
	v_fmac_f32_dpp v241, v29, v185 row_shr:2 row_mask:0xf bank_mask:0xf
; DEV float bf2f(u16 h) { return __uint_as_float(((uint32_t)h) << 16); }
; DEV void gemm_tile(const u16* __restrict__ A, const u16* __restrict__ Bt, u16* __restrict__ C, int N, int K,
;                    int brow, int bcol, unsigned char* smem, int epi, const GateEpi& ge) {
;     ...
;         for (int n = 0; n < 2; ++n) {
;           const int cl = wc * 32 + n * 16 + fr2, cg = pn * 128 + cl;
;           float am2 = 0.f, am1 = 0.f;
;           if (R0 > 0) { am2 = bf2f(sAt[(R0 - 2) * AS + cl]); am1 = bf2f(sAt[(R0 - 1) * AS + cl]); }
; #pragma unroll
;           for (int j = 0; j < 4; ++j) {
;             const float a0 = acc[ai][0][m][n][j], b0 = acc[ai][1][m][n][j];
;             if (R0 > 0 || j >= 2) {
;               const float gv = gelu_tanh(bs[n] + w0[n] * am2 + w1[n] * am1 + w2[n] * a0) * b0;
;               ge.g[(size_t)(brow + R0 + j) * DFF + cg] = f2bf(gv);
;             } else {
;               ge.first_a[((size_t)pm * 2 + j) * DFF + cg] = sAt[(R0 + j) * AS + cl];
;               ge.first_b[((size_t)pm * 2 + j) * DFF + cg] = f2bf(b0);
;             }
;             if (R0 == 252 && j >= 2) ge.halo_a[((size_t)pm * 2 + (j - 2)) * DFF + cg] = sAt[(R0 + j) * AS + cl];
;             am2 = am1; am1 = a0;
	v_fmac_f32_dpp v242, v30, v186 row_shr:2 row_mask:0xf bank_mask:0xf
	v_fmac_f32_dpp v243, v31, v187 row_shr:2 row_mask:0xf bank_mask:0xf
	v_fmac_f32_dpp v244, v24, v188 row_shr:2 row_mask:0xf bank_mask:0xf
	v_fmac_f32_dpp v245, v25, v189 row_shr:2 row_mask:0xf bank_mask:0xf
	v_fmac_f32_dpp v246, v26, v190 row_shr:2 row_mask:0xf bank_mask:0xf
	v_fmac_f32_dpp v247, v27, v191 row_shr:2 row_mask:0xf bank_mask:0xf
	v_fmac_f32_dpp v240, v232, v224 row_ror:2 row_mask:0xf bank_mask:0xf
	v_fmac_f32_dpp v241, v233, v225 row_ror:2 row_mask:0xf bank_mask:0xf
	v_fmac_f32_dpp v242, v234, v226 row_ror:2 row_mask:0xf bank_mask:0xf
	v_fmac_f32_dpp v243, v235, v227 row_ror:2 row_mask:0xf bank_mask:0xf
	v_fmac_f32_dpp v244, v236, v228 row_ror:2 row_mask:0xf bank_mask:0xf
	v_fmac_f32_dpp v245, v237, v229 row_ror:2 row_mask:0xf bank_mask:0xf
	v_fmac_f32_dpp v246, v238, v230 row_ror:2 row_mask:0xf bank_mask:0xf
	v_fmac_f32_dpp v247, v239, v231 row_ror:2 row_mask:0xf bank_mask:0xf
	v_pk_mul_f32 v[248:249], v[240:241], v[240:241]
	v_pk_mul_f32 v[250:251], v[242:243], v[242:243]
	v_pk_mul_f32 v[182:183], v[244:245], v[244:245]
	v_pk_mul_f32 v[154:155], v[246:247], v[246:247]
	v_pk_fma_f32 v[248:249], v[248:249], s[52:53], v[180:181]
	v_pk_fma_f32 v[250:251], v[250:251], s[52:53], v[180:181]
	v_pk_fma_f32 v[182:183], v[182:183], s[52:53], v[180:181]
	v_pk_fma_f32 v[154:155], v[154:155], s[52:53], v[180:181]
	v_pk_mul_f32 v[248:249], v[240:241], v[248:249]
	v_pk_mul_f32 v[250:251], v[242:243], v[250:251]
	v_pk_mul_f32 v[182:183], v[244:245], v[182:183]
	v_pk_mul_f32 v[154:155], v[246:247], v[154:155]
	v_exp_f32_e32 v248, v248
	v_exp_f32_e32 v249, v249
	v_exp_f32_e32 v250, v250
	v_exp_f32_e32 v251, v251
	v_exp_f32_e32 v182, v182
	v_exp_f32_e32 v183, v183
	v_exp_f32_e32 v154, v154
	v_exp_f32_e32 v155, v155
	v_pk_add_f32 v[248:249], v[248:249], s[94:95]
	v_pk_add_f32 v[250:251], v[250:251], s[94:95]
	v_pk_add_f32 v[182:183], v[182:183], s[94:95]
	v_pk_add_f32 v[154:155], v[154:155], s[94:95]
	v_rcp_f32_e32 v248, v248
	v_rcp_f32_e32 v249, v249
	v_rcp_f32_e32 v250, v250
	v_rcp_f32_e32 v251, v251
	v_rcp_f32_e32 v182, v182
	v_rcp_f32_e32 v183, v183
	v_rcp_f32_e32 v154, v154
	v_rcp_f32_e32 v155, v155
	v_pk_mul_f32 v[240:241], v[240:241], v[248:249]
	v_pk_mul_f32 v[242:243], v[242:243], v[250:251]
	v_pk_mul_f32 v[244:245], v[244:245], v[182:183]
	v_pk_mul_f32 v[246:247], v[246:247], v[154:155]
	v_pk_mul_f32 v[240:241], v[240:241], v[56:57]
	v_pk_mul_f32 v[242:243], v[242:243], v[58:59]
	v_pk_mul_f32 v[244:245], v[244:245], v[60:61]
	v_pk_mul_f32 v[246:247], v[246:247], v[62:63]
	v_cvt_pk_bf16_f32 v248, v240, v241
	v_cvt_pk_bf16_f32 v249, v242, v243
	v_cvt_pk_bf16_f32 v250, v244, v245
	v_cvt_pk_bf16_f32 v251, v246, v247
	global_store_dwordx4 v153, v[248:251], s[0:1]
	s_add_u32 s0, s0, 0x2c000
	s_addc_u32 s1, s1, 0
	v_pk_fma_f32 v[240:241], v[200:201], v[20:21], v[208:209]
	v_pk_fma_f32 v[242:243], v[202:203], v[22:23], v[210:211]
	v_pk_fma_f32 v[244:245], v[204:205], v[16:17], v[212:213]
	v_pk_fma_f32 v[246:247], v[206:207], v[18:19], v[214:215]
	v_fmac_f32_dpp v240, v20, v192 row_shr:1 row_mask:0xf bank_mask:0xf
	v_fmac_f32_dpp v241, v21, v193 row_shr:1 row_mask:0xf bank_mask:0xf
	v_fmac_f32_dpp v242, v22, v194 row_shr:1 row_mask:0xf bank_mask:0xf
	v_fmac_f32_dpp v243, v23, v195 row_shr:1 row_mask:0xf bank_mask:0xf
	v_fmac_f32_dpp v244, v16, v196 row_shr:1 row_mask:0xf bank_mask:0xf
	v_fmac_f32_dpp v245, v17, v197 row_shr:1 row_mask:0xf bank_mask:0xf
	v_fmac_f32_dpp v246, v18, v198 row_shr:1 row_mask:0xf bank_mask:0xf
	v_fmac_f32_dpp v247, v19, v199 row_shr:1 row_mask:0xf bank_mask:0xf
	v_fmac_f32_dpp v240, v28, v216 row_ror:1 row_mask:0xf bank_mask:0xf
	v_fmac_f32_dpp v241, v29, v217 row_ror:1 row_mask:0xf bank_mask:0xf
	v_fmac_f32_dpp v242, v30, v218 row_ror:1 row_mask:0xf bank_mask:0xf
	v_fmac_f32_dpp v243, v31, v219 row_ror:1 row_mask:0xf bank_mask:0xf
	v_fmac_f32_dpp v244, v24, v220 row_ror:1 row_mask:0xf bank_mask:0xf
	v_fmac_f32_dpp v245, v25, v221 row_ror:1 row_mask:0xf bank_mask:0xf
	v_fmac_f32_dpp v246, v26, v222 row_ror:1 row_mask:0xf bank_mask:0xf
	v_fmac_f32_dpp v247, v27, v223 row_ror:1 row_mask:0xf bank_mask:0xf
	v_fmac_f32_dpp v240, v20, v184 row_shr:2 row_mask:0xf bank_mask:0xf
	v_fmac_f32_dpp v241, v21, v185 row_shr:2 row_mask:0xf bank_mask:0xf
	v_fmac_f32_dpp v242, v22, v186 row_shr:2 row_mask:0xf bank_mask:0xf
	v_fmac_f32_dpp v243, v23, v187 row_shr:2 row_mask:0xf bank_mask:0xf
	v_fmac_f32_dpp v244, v16, v188 row_shr:2 row_mask:0xf bank_mask:0xf
	v_fmac_f32_dpp v245, v17, v189 row_shr:2 row_mask:0xf bank_mask:0xf
	v_fmac_f32_dpp v246, v18, v190 row_shr:2 row_mask:0xf bank_mask:0xf
	v_fmac_f32_dpp v247, v19, v191 row_shr:2 row_mask:0xf bank_mask:0xf
	v_fmac_f32_dpp v240, v28, v224 row_ror:2 row_mask:0xf bank_mask:0xf
	v_fmac_f32_dpp v241, v29, v225 row_ror:2 row_mask:0xf bank_mask:0xf
	v_fmac_f32_dpp v242, v30, v226 row_ror:2 row_mask:0xf bank_mask:0xf
	v_fmac_f32_dpp v243, v31, v227 row_ror:2 row_mask:0xf bank_mask:0xf
	v_fmac_f32_dpp v244, v24, v228 row_ror:2 row_mask:0xf bank_mask:0xf
	v_fmac_f32_dpp v245, v25, v229 row_ror:2 row_mask:0xf bank_mask:0xf
	v_fmac_f32_dpp v246, v26, v230 row_ror:2 row_mask:0xf bank_mask:0xf
	v_fmac_f32_dpp v247, v27, v231 row_ror:2 row_mask:0xf bank_mask:0xf
	v_pk_mul_f32 v[248:249], v[240:241], v[240:241]
	v_pk_mul_f32 v[250:251], v[242:243], v[242:243]
	v_pk_mul_f32 v[182:183], v[244:245], v[244:245]
	v_pk_mul_f32 v[154:155], v[246:247], v[246:247]
	v_pk_fma_f32 v[248:249], v[248:249], s[52:53], v[180:181]
	v_pk_fma_f32 v[250:251], v[250:251], s[52:53], v[180:181]
	v_pk_fma_f32 v[182:183], v[182:183], s[52:53], v[180:181]
; DEV float bf2f(u16 h) { return __uint_as_float(((uint32_t)h) << 16); }
; DEV void gemm_tile(const u16* __restrict__ A, const u16* __restrict__ Bt, u16* __restrict__ C, int N, int K,
;                    int brow, int bcol, unsigned char* smem, int epi, const GateEpi& ge) {
;     ...
;         for (int n = 0; n < 2; ++n) {
;           const int cl = wc * 32 + n * 16 + fr2, cg = pn * 128 + cl;
;           float am2 = 0.f, am1 = 0.f;
;           if (R0 > 0) { am2 = bf2f(sAt[(R0 - 2) * AS + cl]); am1 = bf2f(sAt[(R0 - 1) * AS + cl]); }
; #pragma unroll
;           for (int j = 0; j < 4; ++j) {
;             const float a0 = acc[ai][0][m][n][j], b0 = acc[ai][1][m][n][j];
;             if (R0 > 0 || j >= 2) {
;               const float gv = gelu_tanh(bs[n] + w0[n] * am2 + w1[n] * am1 + w2[n] * a0) * b0;
;               ge.g[(size_t)(brow + R0 + j) * DFF + cg] = f2bf(gv);
;             } else {
;               ge.first_a[((size_t)pm * 2 + j) * DFF + cg] = sAt[(R0 + j) * AS + cl];
;               ge.first_b[((size_t)pm * 2 + j) * DFF + cg] = f2bf(b0);
;             }
;             if (R0 == 252 && j >= 2) ge.halo_a[((size_t)pm * 2 + (j - 2)) * DFF + cg] = sAt[(R0 + j) * AS + cl];
;             am2 = am1; am1 = a0;
	v_pk_fma_f32 v[154:155], v[154:155], s[52:53], v[180:181]
	v_pk_mul_f32 v[248:249], v[240:241], v[248:249]
	v_pk_mul_f32 v[250:251], v[242:243], v[250:251]
	v_pk_mul_f32 v[182:183], v[244:245], v[182:183]
	v_pk_mul_f32 v[154:155], v[246:247], v[154:155]
	v_exp_f32_e32 v248, v248
	v_exp_f32_e32 v249, v249
	v_exp_f32_e32 v250, v250
	v_exp_f32_e32 v251, v251
	v_exp_f32_e32 v182, v182
	v_exp_f32_e32 v183, v183
	v_exp_f32_e32 v154, v154
	v_exp_f32_e32 v155, v155
	v_pk_add_f32 v[248:249], v[248:249], s[94:95]
	v_pk_add_f32 v[250:251], v[250:251], s[94:95]
	v_pk_add_f32 v[182:183], v[182:183], s[94:95]
	v_pk_add_f32 v[154:155], v[154:155], s[94:95]
	v_rcp_f32_e32 v248, v248
	v_rcp_f32_e32 v249, v249
	v_rcp_f32_e32 v250, v250
	v_rcp_f32_e32 v251, v251
	v_rcp_f32_e32 v182, v182
	v_rcp_f32_e32 v183, v183
	v_rcp_f32_e32 v154, v154
	v_rcp_f32_e32 v155, v155
	v_pk_mul_f32 v[240:241], v[240:241], v[248:249]
	v_pk_mul_f32 v[242:243], v[242:243], v[250:251]
	v_pk_mul_f32 v[244:245], v[244:245], v[182:183]
	v_pk_mul_f32 v[246:247], v[246:247], v[154:155]
	v_pk_mul_f32 v[240:241], v[240:241], v[64:65]
	v_pk_mul_f32 v[242:243], v[242:243], v[66:67]
	v_pk_mul_f32 v[244:245], v[244:245], v[72:73]
	v_pk_mul_f32 v[246:247], v[246:247], v[74:75]
	v_cvt_pk_bf16_f32 v248, v240, v241
	v_cvt_pk_bf16_f32 v249, v242, v243
	v_cvt_pk_bf16_f32 v250, v244, v245
	v_cvt_pk_bf16_f32 v251, v246, v247
	global_store_dwordx4 v153, v[248:251], s[0:1]
	s_add_u32 s0, s0, 0x2c000
	s_addc_u32 s1, s1, 0
	v_pk_fma_f32 v[240:241], v[200:201], v[12:13], v[208:209]
	v_pk_fma_f32 v[242:243], v[202:203], v[14:15], v[210:211]
	v_pk_fma_f32 v[244:245], v[204:205], v[8:9], v[212:213]
	v_pk_fma_f32 v[246:247], v[206:207], v[10:11], v[214:215]
	v_fmac_f32_dpp v240, v12, v192 row_shr:1 row_mask:0xf bank_mask:0xf
	v_fmac_f32_dpp v241, v13, v193 row_shr:1 row_mask:0xf bank_mask:0xf
	v_fmac_f32_dpp v242, v14, v194 row_shr:1 row_mask:0xf bank_mask:0xf
	v_fmac_f32_dpp v243, v15, v195 row_shr:1 row_mask:0xf bank_mask:0xf
	v_fmac_f32_dpp v244, v8, v196 row_shr:1 row_mask:0xf bank_mask:0xf
	v_fmac_f32_dpp v245, v9, v197 row_shr:1 row_mask:0xf bank_mask:0xf
	v_fmac_f32_dpp v246, v10, v198 row_shr:1 row_mask:0xf bank_mask:0xf
	v_fmac_f32_dpp v247, v11, v199 row_shr:1 row_mask:0xf bank_mask:0xf
	v_fmac_f32_dpp v240, v20, v216 row_ror:1 row_mask:0xf bank_mask:0xf
	v_fmac_f32_dpp v241, v21, v217 row_ror:1 row_mask:0xf bank_mask:0xf
	v_fmac_f32_dpp v242, v22, v218 row_ror:1 row_mask:0xf bank_mask:0xf
	v_fmac_f32_dpp v243, v23, v219 row_ror:1 row_mask:0xf bank_mask:0xf
	v_fmac_f32_dpp v244, v16, v220 row_ror:1 row_mask:0xf bank_mask:0xf
	v_fmac_f32_dpp v245, v17, v221 row_ror:1 row_mask:0xf bank_mask:0xf
	v_fmac_f32_dpp v246, v18, v222 row_ror:1 row_mask:0xf bank_mask:0xf
	v_fmac_f32_dpp v247, v19, v223 row_ror:1 row_mask:0xf bank_mask:0xf
	v_fmac_f32_dpp v240, v12, v184 row_shr:2 row_mask:0xf bank_mask:0xf
	v_fmac_f32_dpp v241, v13, v185 row_shr:2 row_mask:0xf bank_mask:0xf
	v_fmac_f32_dpp v242, v14, v186 row_shr:2 row_mask:0xf bank_mask:0xf
	v_fmac_f32_dpp v243, v15, v187 row_shr:2 row_mask:0xf bank_mask:0xf
	v_fmac_f32_dpp v244, v8, v188 row_shr:2 row_mask:0xf bank_mask:0xf
	v_fmac_f32_dpp v245, v9, v189 row_shr:2 row_mask:0xf bank_mask:0xf
	v_fmac_f32_dpp v246, v10, v190 row_shr:2 row_mask:0xf bank_mask:0xf
	v_fmac_f32_dpp v247, v11, v191 row_shr:2 row_mask:0xf bank_mask:0xf
	v_fmac_f32_dpp v240, v20, v224 row_ror:2 row_mask:0xf bank_mask:0xf
	v_fmac_f32_dpp v241, v21, v225 row_ror:2 row_mask:0xf bank_mask:0xf
	v_fmac_f32_dpp v242, v22, v226 row_ror:2 row_mask:0xf bank_mask:0xf
	v_fmac_f32_dpp v243, v23, v227 row_ror:2 row_mask:0xf bank_mask:0xf
	v_fmac_f32_dpp v244, v16, v228 row_ror:2 row_mask:0xf bank_mask:0xf
	v_fmac_f32_dpp v245, v17, v229 row_ror:2 row_mask:0xf bank_mask:0xf
	v_fmac_f32_dpp v246, v18, v230 row_ror:2 row_mask:0xf bank_mask:0xf
	v_fmac_f32_dpp v247, v19, v231 row_ror:2 row_mask:0xf bank_mask:0xf
	v_pk_mul_f32 v[248:249], v[240:241], v[240:241]
	v_pk_mul_f32 v[250:251], v[242:243], v[242:243]
	v_pk_mul_f32 v[182:183], v[244:245], v[244:245]
	v_pk_mul_f32 v[154:155], v[246:247], v[246:247]
	v_pk_fma_f32 v[248:249], v[248:249], s[52:53], v[180:181]
	v_pk_fma_f32 v[250:251], v[250:251], s[52:53], v[180:181]
	v_pk_fma_f32 v[182:183], v[182:183], s[52:53], v[180:181]
	v_pk_fma_f32 v[154:155], v[154:155], s[52:53], v[180:181]
	v_pk_mul_f32 v[248:249], v[240:241], v[248:249]
	v_pk_mul_f32 v[250:251], v[242:243], v[250:251]
	v_pk_mul_f32 v[182:183], v[244:245], v[182:183]
	v_pk_mul_f32 v[154:155], v[246:247], v[154:155]
	v_exp_f32_e32 v248, v248
	v_exp_f32_e32 v249, v249
	v_exp_f32_e32 v250, v250
	v_exp_f32_e32 v251, v251
	v_exp_f32_e32 v182, v182
	v_exp_f32_e32 v183, v183
	v_exp_f32_e32 v154, v154
	v_exp_f32_e32 v155, v155
	v_pk_add_f32 v[248:249], v[248:249], s[94:95]
	v_pk_add_f32 v[250:251], v[250:251], s[94:95]
	v_pk_add_f32 v[182:183], v[182:183], s[94:95]
	v_pk_add_f32 v[154:155], v[154:155], s[94:95]
	v_rcp_f32_e32 v248, v248
	v_rcp_f32_e32 v249, v249
	v_rcp_f32_e32 v250, v250
	v_rcp_f32_e32 v251, v251
	v_rcp_f32_e32 v182, v182
	v_rcp_f32_e32 v183, v183
	v_rcp_f32_e32 v154, v154
	v_rcp_f32_e32 v155, v155
	v_pk_mul_f32 v[240:241], v[240:241], v[248:249]
	v_pk_mul_f32 v[242:243], v[242:243], v[250:251]
	v_pk_mul_f32 v[244:245], v[244:245], v[182:183]
	v_pk_mul_f32 v[246:247], v[246:247], v[154:155]
	v_pk_mul_f32 v[240:241], v[240:241], v[76:77]
	v_pk_mul_f32 v[242:243], v[242:243], v[78:79]
	v_pk_mul_f32 v[244:245], v[244:245], v[80:81]
	v_pk_mul_f32 v[246:247], v[246:247], v[82:83]
	v_cvt_pk_bf16_f32 v248, v240, v241
	v_cvt_pk_bf16_f32 v249, v242, v243
	v_cvt_pk_bf16_f32 v250, v244, v245
; DEV float bf2f(u16 h) { return __uint_as_float(((uint32_t)h) << 16); }
; DEV void gemm_tile(const u16* __restrict__ A, const u16* __restrict__ Bt, u16* __restrict__ C, int N, int K,
;                    int brow, int bcol, unsigned char* smem, int epi, const GateEpi& ge) {
;     ...
;         for (int n = 0; n < 2; ++n) {
;           const int cl = wc * 32 + n * 16 + fr2, cg = pn * 128 + cl;
;           float am2 = 0.f, am1 = 0.f;
;           if (R0 > 0) { am2 = bf2f(sAt[(R0 - 2) * AS + cl]); am1 = bf2f(sAt[(R0 - 1) * AS + cl]); }
; #pragma unroll
;           for (int j = 0; j < 4; ++j) {
;             const float a0 = acc[ai][0][m][n][j], b0 = acc[ai][1][m][n][j];
;             if (R0 > 0 || j >= 2) {
;               const float gv = gelu_tanh(bs[n] + w0[n] * am2 + w1[n] * am1 + w2[n] * a0) * b0;
;               ge.g[(size_t)(brow + R0 + j) * DFF + cg] = f2bf(gv);
;             } else {
;               ge.first_a[((size_t)pm * 2 + j) * DFF + cg] = sAt[(R0 + j) * AS + cl];
;               ge.first_b[((size_t)pm * 2 + j) * DFF + cg] = f2bf(b0);
;             }
;             if (R0 == 252 && j >= 2) ge.halo_a[((size_t)pm * 2 + (j - 2)) * DFF + cg] = sAt[(R0 + j) * AS + cl];
;             am2 = am1; am1 = a0;
	v_cvt_pk_bf16_f32 v251, v246, v247
	global_store_dwordx4 v153, v[248:251], s[0:1]
	s_add_u32 s0, s0, 0x2c000
	s_addc_u32 s1, s1, 0
	v_pk_fma_f32 v[240:241], v[200:201], v[4:5], v[208:209]
	v_pk_fma_f32 v[242:243], v[202:203], v[6:7], v[210:211]
	v_pk_fma_f32 v[244:245], v[204:205], v[0:1], v[212:213]
	v_pk_fma_f32 v[246:247], v[206:207], v[2:3], v[214:215]
	v_fmac_f32_dpp v240, v4, v192 row_shr:1 row_mask:0xf bank_mask:0xf
	v_fmac_f32_dpp v241, v5, v193 row_shr:1 row_mask:0xf bank_mask:0xf
	v_fmac_f32_dpp v242, v6, v194 row_shr:1 row_mask:0xf bank_mask:0xf
	v_fmac_f32_dpp v243, v7, v195 row_shr:1 row_mask:0xf bank_mask:0xf
	v_fmac_f32_dpp v244, v0, v196 row_shr:1 row_mask:0xf bank_mask:0xf
	v_fmac_f32_dpp v245, v1, v197 row_shr:1 row_mask:0xf bank_mask:0xf
	v_fmac_f32_dpp v246, v2, v198 row_shr:1 row_mask:0xf bank_mask:0xf
	v_fmac_f32_dpp v247, v3, v199 row_shr:1 row_mask:0xf bank_mask:0xf
	v_fmac_f32_dpp v240, v12, v216 row_ror:1 row_mask:0xf bank_mask:0xf
	v_fmac_f32_dpp v241, v13, v217 row_ror:1 row_mask:0xf bank_mask:0xf
	v_fmac_f32_dpp v242, v14, v218 row_ror:1 row_mask:0xf bank_mask:0xf
	v_fmac_f32_dpp v243, v15, v219 row_ror:1 row_mask:0xf bank_mask:0xf
	v_fmac_f32_dpp v244, v8, v220 row_ror:1 row_mask:0xf bank_mask:0xf
	v_fmac_f32_dpp v245, v9, v221 row_ror:1 row_mask:0xf bank_mask:0xf
	v_fmac_f32_dpp v246, v10, v222 row_ror:1 row_mask:0xf bank_mask:0xf
	v_fmac_f32_dpp v247, v11, v223 row_ror:1 row_mask:0xf bank_mask:0xf
	v_fmac_f32_dpp v240, v4, v184 row_shr:2 row_mask:0xf bank_mask:0xf
	v_fmac_f32_dpp v241, v5, v185 row_shr:2 row_mask:0xf bank_mask:0xf
	v_fmac_f32_dpp v242, v6, v186 row_shr:2 row_mask:0xf bank_mask:0xf
	v_fmac_f32_dpp v243, v7, v187 row_shr:2 row_mask:0xf bank_mask:0xf
	v_fmac_f32_dpp v244, v0, v188 row_shr:2 row_mask:0xf bank_mask:0xf
	v_fmac_f32_dpp v245, v1, v189 row_shr:2 row_mask:0xf bank_mask:0xf
	v_fmac_f32_dpp v246, v2, v190 row_shr:2 row_mask:0xf bank_mask:0xf
	v_fmac_f32_dpp v247, v3, v191 row_shr:2 row_mask:0xf bank_mask:0xf
	v_fmac_f32_dpp v240, v12, v224 row_ror:2 row_mask:0xf bank_mask:0xf
	v_fmac_f32_dpp v241, v13, v225 row_ror:2 row_mask:0xf bank_mask:0xf
	v_fmac_f32_dpp v242, v14, v226 row_ror:2 row_mask:0xf bank_mask:0xf
	v_fmac_f32_dpp v243, v15, v227 row_ror:2 row_mask:0xf bank_mask:0xf
	v_fmac_f32_dpp v244, v8, v228 row_ror:2 row_mask:0xf bank_mask:0xf
	v_fmac_f32_dpp v245, v9, v229 row_ror:2 row_mask:0xf bank_mask:0xf
	v_fmac_f32_dpp v246, v10, v230 row_ror:2 row_mask:0xf bank_mask:0xf
	v_fmac_f32_dpp v247, v11, v231 row_ror:2 row_mask:0xf bank_mask:0xf
	v_pk_mul_f32 v[248:249], v[240:241], v[240:241]
	v_pk_mul_f32 v[250:251], v[242:243], v[242:243]
	v_pk_mul_f32 v[182:183], v[244:245], v[244:245]
	v_pk_mul_f32 v[154:155], v[246:247], v[246:247]
	v_pk_fma_f32 v[248:249], v[248:249], s[52:53], v[180:181]
	v_pk_fma_f32 v[250:251], v[250:251], s[52:53], v[180:181]
	v_pk_fma_f32 v[182:183], v[182:183], s[52:53], v[180:181]
	v_pk_fma_f32 v[154:155], v[154:155], s[52:53], v[180:181]
	v_pk_mul_f32 v[248:249], v[240:241], v[248:249]
	v_pk_mul_f32 v[250:251], v[242:243], v[250:251]
	v_pk_mul_f32 v[182:183], v[244:245], v[182:183]
	v_pk_mul_f32 v[154:155], v[246:247], v[154:155]
	v_exp_f32_e32 v248, v248
	v_exp_f32_e32 v249, v249
	v_exp_f32_e32 v250, v250
	v_exp_f32_e32 v251, v251
	v_exp_f32_e32 v182, v182
	v_exp_f32_e32 v183, v183
	v_exp_f32_e32 v154, v154
	v_exp_f32_e32 v155, v155
	v_pk_add_f32 v[248:249], v[248:249], s[94:95]
	v_pk_add_f32 v[250:251], v[250:251], s[94:95]
	v_pk_add_f32 v[182:183], v[182:183], s[94:95]
	v_pk_add_f32 v[154:155], v[154:155], s[94:95]
	v_rcp_f32_e32 v248, v248
	v_rcp_f32_e32 v249, v249
	v_rcp_f32_e32 v250, v250
	v_rcp_f32_e32 v251, v251
	v_rcp_f32_e32 v182, v182
	v_rcp_f32_e32 v183, v183
	v_rcp_f32_e32 v154, v154
	v_rcp_f32_e32 v155, v155
	v_pk_mul_f32 v[240:241], v[240:241], v[248:249]
	v_pk_mul_f32 v[242:243], v[242:243], v[250:251]
	v_pk_mul_f32 v[244:245], v[244:245], v[182:183]
	v_pk_mul_f32 v[246:247], v[246:247], v[154:155]
	v_pk_mul_f32 v[240:241], v[240:241], v[88:89]
	v_pk_mul_f32 v[242:243], v[242:243], v[90:91]
	v_pk_mul_f32 v[244:245], v[244:245], v[92:93]
	v_pk_mul_f32 v[246:247], v[246:247], v[94:95]
	v_cvt_pk_bf16_f32 v248, v240, v241
	v_cvt_pk_bf16_f32 v249, v242, v243
	v_cvt_pk_bf16_f32 v250, v244, v245
	v_cvt_pk_bf16_f32 v251, v246, v247
	global_store_dwordx4 v153, v[248:251], s[0:1]
	s_cmp_lg_u32 s34, 1
	s_cbranch_scc1 .Lg_post
	s_mov_b32 exec_lo, 0xc000c000
	s_mov_b32 exec_hi, 0xc000c000
	v_cvt_pk_bf16_f32 v240, v4, v5
	v_cvt_pk_bf16_f32 v241, v6, v7
	v_cvt_pk_bf16_f32 v242, v0, v1
	v_cvt_pk_bf16_f32 v243, v2, v3
	global_store_dwordx4 v153, v[240:243], s[54:55]
	s_mov_b64 exec, -1
; #define STAGE(P, q) do { GLDS16(q[0], (unsigned char*)(P) + wid * 1024); GLDS16(q[1], (unsigned char*)(P) + wid * 1024 + 8192); \
;     q[0] += 128; q[1] += 128; asm volatile("" : "+v"(q[0]), "+v"(q[1])); } while (0)
; #define WAIT_V(n) asm volatile("s_waitcnt vmcnt(" #n ")" ::: "memory")
; #define WAIT_L(n) asm volatile("s_waitcnt lgkmcnt(" #n ")" ::: "memory")
; #define BAR __builtin_amdgcn_s_barrier()
; DEV void gemm_tile(const u16* __restrict__ A, const u16* __restrict__ Bt, u16* __restrict__ C, int N, int K,
;                    int brow, int bcol, unsigned char* smem, int epi, const GateEpi& ge) {
;     ...
;   f32x4 acc[2][2][4][2];
; #pragma unroll
;   for (int a = 0; a < 2; ++a)
; #pragma unroll
;     for (int b = 0; b < 2; ++b)
; #pragma unroll
;       for (int m = 0; m < 4; ++m)
; #pragma unroll
;         for (int n = 0; n < 2; ++n) acc[a][b][m][n] = (f32x4){0.f, 0.f, 0.f, 0.f};
;   bf16x8 At[4][2], B0[2][2], B1[2][2];
;   const int nt = K / 64;
;   WAIT_L(0);
;   __syncthreads();
;   STAGE(SB(0, 0), qB0); STAGE(SA(0, 0), qA0);
;   STAGE(SB(0, 1), qB1); STAGE(SA(0, 1), qA1);
;   if (wr == 1) BAR;
;   WAIT_V(4); BAR;
;   STAGE(SB(1, 0), qB0); STAGE(SA(1, 0), qA0); STAGE(SB(1, 1), qB1);
;   WAIT_V(6); BAR;
; DEV void phase_gemm(const u16* A, const u16* Bt, u16* C, int ntiles, int N, int K, unsigned char* smem, int epi, const GateEpi& ge) {
;     ...
;   for (int t = lb; t < ntiles; t += gridDim.x) {
;     while (rem >= nig) { rem -= nig; ++gid; }
;     const int pm = gid * 8 + (rem & 7), pn = rem >> 3;
;     gemm_tile(A, Bt, C, N, K, pm * 256, pn * 256, smem, epi, ge);
;     rem += gridDim.x;
.Lg_post:
	s_cmp_eq_u32 s63, 0
	s_cbranch_scc1 .LBB0_818
	v_mov_b64_e32 v[0:1], 0
	v_mov_b64_e32 v[2:3], 0
	v_mov_b64_e32 v[4:5], 0
	v_mov_b64_e32 v[6:7], 0
	v_mov_b64_e32 v[8:9], 0
	v_mov_b64_e32 v[10:11], 0
	v_mov_b64_e32 v[12:13], 0
	v_mov_b64_e32 v[14:15], 0
	v_mov_b64_e32 v[16:17], 0
	v_mov_b64_e32 v[18:19], 0
	v_mov_b64_e32 v[20:21], 0
	v_mov_b64_e32 v[22:23], 0
	v_mov_b64_e32 v[24:25], 0
	v_mov_b64_e32 v[26:27], 0
	v_mov_b64_e32 v[28:29], 0
	v_mov_b64_e32 v[30:31], 0
	v_mov_b64_e32 v[32:33], 0
	v_mov_b64_e32 v[34:35], 0
	v_mov_b64_e32 v[36:37], 0
	v_mov_b64_e32 v[38:39], 0
	v_mov_b64_e32 v[40:41], 0
	v_mov_b64_e32 v[42:43], 0
	v_mov_b64_e32 v[44:45], 0
	v_mov_b64_e32 v[46:47], 0
	v_mov_b64_e32 v[48:49], 0
	v_mov_b64_e32 v[50:51], 0
	v_mov_b64_e32 v[52:53], 0
	v_mov_b64_e32 v[54:55], 0
	v_mov_b64_e32 v[56:57], 0
	v_mov_b64_e32 v[58:59], 0
	v_mov_b64_e32 v[60:61], 0
	v_mov_b64_e32 v[62:63], 0
	v_mov_b64_e32 v[64:65], 0
	v_mov_b64_e32 v[66:67], 0
	v_mov_b64_e32 v[68:69], 0
	v_mov_b64_e32 v[70:71], 0
	v_mov_b64_e32 v[72:73], 0
	v_mov_b64_e32 v[74:75], 0
	v_mov_b64_e32 v[76:77], 0
	v_mov_b64_e32 v[78:79], 0
	v_mov_b64_e32 v[80:81], 0
	v_mov_b64_e32 v[82:83], 0
	v_mov_b64_e32 v[84:85], 0
	v_mov_b64_e32 v[86:87], 0
	v_mov_b64_e32 v[88:89], 0
	v_mov_b64_e32 v[90:91], 0
	v_mov_b64_e32 v[92:93], 0
	v_mov_b64_e32 v[94:95], 0
	v_mov_b64_e32 v[96:97], 0
	v_mov_b64_e32 v[98:99], 0
	v_mov_b64_e32 v[100:101], 0
	v_mov_b64_e32 v[102:103], 0
	v_mov_b64_e32 v[104:105], 0
	v_mov_b64_e32 v[106:107], 0
	v_mov_b64_e32 v[108:109], 0
	v_mov_b64_e32 v[110:111], 0
	v_mov_b64_e32 v[112:113], 0
	v_mov_b64_e32 v[114:115], 0
	v_mov_b64_e32 v[116:117], 0
	v_mov_b64_e32 v[118:119], 0
	v_mov_b64_e32 v[120:121], 0
	v_mov_b64_e32 v[122:123], 0
	v_mov_b64_e32 v[124:125], 0
	v_mov_b64_e32 v[126:127], 0
	s_add_i32 s48, s48, s33
	v_readlane_b32 s47, v252, 42
	v_readlane_b32 s46, v252, 43
	s_lshl_b32 s0, s47, 8
	s_and_b32 s0, s0, 0x700
	s_lshl_b32 s1, s46, 11
	s_or_b32 s49, s1, s0
	s_lshl_b32 s0, s47, 5
	s_and_b32 s92, s0, 0xffffff00
	s_ashr_i32 s93, s92, 31
	s_lshl_b32 s1, s34, 2
	s_add_i32 s1, s1, s50
	s_lshl_b32 s1, s1, 10
	s_add_i32 s56, s1, 0xc000
	s_add_i32 s52, s1, 0xe000
	s_add_i32 s4, s1, 0x10000
	s_add_i32 s5, s1, 0x12000
	s_add_i32 s6, s1, 0x2000
	s_add_i32 s7, s1, 0x14000
	s_add_i32 s35, s1, 0x16000
	s_add_i32 s41, s1, 0x4000
	s_add_i32 vcc_lo, s1, 0x6000
	s_add_i32 vcc_hi, s1, 0x18000
	s_add_i32 s28, s1, 0x1a000
	s_add_i32 s94, s1, 0x8000
	s_add_i32 s95, s1, 0xa000
	s_add_i32 s62, s1, 0x1c000
	s_add_i32 s63, s1, 0x1e000
	s_lshl_b32 s59, s34, 13
	s_or_b32 s53, s59, 0x800
	s_or_b32 s54, s59, 0x1000
	s_or_b32 s55, s59, 0x1800
	s_mov_b32 s57, 0
	s_cmp_lg_u32 s34, 1
	s_cbranch_scc1 .Lg_nostag
	s_barrier
.Lg_nostag:
	s_branch .LBB0_634
.LBB0_818:
	v_readlane_b32 s14, v252, 37
	s_add_i32 s12, s14, 1
	s_cmp_eq_u32 s14, 19
	s_cbranch_scc1 .LBB0_155
	s_waitcnt vmcnt(0)
	s_waitcnt vmcnt(0) lgkmcnt(0)
	s_barrier
	s_mov_b64 s[0:1], exec
	v_readlane_b32 s2, v253, 4
	v_readlane_b32 s3, v253, 5
	s_and_b64 s[2:3], s[0:1], s[2:3]
	s_mov_b64 exec, s[2:3]
	s_cbranch_execz .LBB0_154
	s_mov_b64 s[2:3], exec
	v_mbcnt_lo_u32_b32 v0, s2, 0
	v_mbcnt_hi_u32_b32 v0, s3, v0
	v_cmp_eq_u32_e32 vcc, 0, v0
	s_waitcnt vmcnt(0) expcnt(0) lgkmcnt(0)
	s_and_saveexec_b64 s[4:5], vcc
	s_cbranch_execz .LBB0_822
	s_bcnt1_i32_b64 s2, s[2:3]
	v_mov_b32_e32 v1, s2
	v_readlane_b32 s2, v252, 3
	v_readlane_b32 s3, v252, 4
	s_nop 4
	global_atomic_add v1, v129, v1, s[2:3] sc0

; __global__ void __launch_bounds__(NT, 2) k_mega(Params p) {
;   __shared__ __attribute__((aligned(1024))) unsigned char smem[LDS_BYTES];
	.amdhsa_kernel _Z6k_mega6Params
		.amdhsa_group_segment_fixed_size 135168
		.amdhsa_private_segment_fixed_size 0
		.amdhsa_kernarg_size 504
		.amdhsa_user_sgpr_count 2
		.amdhsa_user_sgpr_dispatch_ptr 0
		.amdhsa_user_sgpr_queue_ptr 0
		.amdhsa_user_sgpr_kernarg_segment_ptr 1
		.amdhsa_user_sgpr_dispatch_id 0
		.amdhsa_user_sgpr_kernarg_preload_length 0
		.amdhsa_user_sgpr_kernarg_preload_offset 0
		.amdhsa_user_sgpr_private_segment_size 0
		.amdhsa_uses_dynamic_stack 0
		.amdhsa_enable_private_segment 0
		.amdhsa_system_sgpr_workgroup_id_x 1
		.amdhsa_system_sgpr_workgroup_id_y 0
		.amdhsa_system_sgpr_workgroup_id_z 0
		.amdhsa_system_sgpr_workgroup_info 0
		.amdhsa_system_vgpr_workitem_id 2
		.amdhsa_next_free_vgpr 254
		.amdhsa_next_free_sgpr 100
		.amdhsa_accum_offset 256
		.amdhsa_reserve_vcc 1
		.amdhsa_float_round_mode_32 0
		.amdhsa_float_round_mode_16_64 0
		.amdhsa_float_denorm_mode_32 3
		.amdhsa_float_denorm_mode_16_64 3
		.amdhsa_dx10_clamp 1
		.amdhsa_ieee_mode 1
		.amdhsa_fp16_overflow 0
		.amdhsa_tg_split 0
		.amdhsa_exception_fp_ieee_invalid_op 0
		.amdhsa_exception_fp_denorm_src 0
		.amdhsa_exception_fp_ieee_div_zero 0
		.amdhsa_exception_fp_ieee_overflow 0
		.amdhsa_exception_fp_ieee_underflow 0
		.amdhsa_exception_fp_ieee_inexact 0
		.amdhsa_exception_int_div_zero 0
	.end_amdhsa_kernel

; __global__ void __launch_bounds__(NT, 2) k_mega(Params p) {
;   __shared__ __attribute__((aligned(1024))) unsigned char smem[LDS_BYTES];
amdhsa.kernels:
  - .agpr_count:     0
    .args:
      - .offset:         0
        .size:           248
        .value_kind:     by_value
      - .offset:         248
        .size:           4
        .value_kind:     hidden_block_count_x
      - .offset:         252
        .size:           4
        .value_kind:     hidden_block_count_y
      - .offset:         256
        .size:           4
        .value_kind:     hidden_block_count_z
      - .offset:         260
        .size:           2
        .value_kind:     hidden_group_size_x
      - .offset:         262
        .size:           2
        .value_kind:     hidden_group_size_y
      - .offset:         264
        .size:           2
        .value_kind:     hidden_group_size_z
      - .offset:         266
        .size:           2
        .value_kind:     hidden_remainder_x
      - .offset:         268
        .size:           2
        .value_kind:     hidden_remainder_y
      - .offset:         270
        .size:           2
        .value_kind:     hidden_remainder_z
      - .offset:         288
        .size:           8
        .value_kind:     hidden_global_offset_x
      - .offset:         296
        .size:           8
        .value_kind:     hidden_global_offset_y
      - .offset:         304
        .size:           8
        .value_kind:     hidden_global_offset_z
      - .offset:         312
        .size:           2
        .value_kind:     hidden_grid_dims
      - .offset:         336
        .size:           8
        .value_kind:     hidden_multigrid_sync_arg
    .group_segment_fixed_size: 135168
    .kernarg_segment_align: 8
    .kernarg_segment_size: 504
    .language:       OpenCL C
    .language_version:
      - 2
      - 0
    .max_flat_workgroup_size: 512
    .name:           _Z6k_mega6Params
    .private_segment_fixed_size: 0
    .sgpr_count:     106
    .sgpr_spill_count: 107
    .symbol:         _Z6k_mega6Params.kd
    .uniform_work_group_size: 1
    .uses_dynamic_stack: false
    .vgpr_count:     254
    .vgpr_spill_count: 0
    .wavefront_size: 64
